# v8: v7 + 184 gate/up weight slabs moved from P0 (HBM-bound) to the P1 tail's idle CUs (SLAB0 412->228, 5 slabs per idle CU)
# baseline (speedup 1.0000x reference)
.LBB0_18:
	s_or_b64 exec, exec, s[24:25]
	s_lshl_b32 s4, s3, 7
	s_add_i32 s4, s4, 0
	s_lshl_b32 s63, s3, 9
	s_add_i32 s72, s4, 0x16000
	s_mov_b32 s7, 0
	s_cmpk_gt_i32 s2, 0x163
	v_lshlrev_b32_e32 v84, 2, v128
	s_waitcnt lgkmcnt(0)
	s_barrier
	s_cbranch_scc1 .LBB0_34
	s_lshl_b32 s5, s3, 5
	s_and_b32 s4, s63, 0x7ffff800
	s_and_b32 s5, s5, 0x60
	v_ashrrev_i32_e32 v0, 1, v128
	s_or_b32 s4, s4, s5
	v_and_b32_e32 v0, -4, v0
	v_and_b32_e32 v64, 28, v84
	v_add_u32_e32 v0, s4, v0
	v_lshlrev_b32_e32 v66, 2, v64
	v_mov_b32_e32 v67, 0
	v_lshl_add_u64 v[2:3], s[18:19], 0, v[66:67]
	s_mov_b64 s[26:27], 0xb8000
	v_ashrrev_i32_e32 v1, 31, v0
	v_lshl_add_u64 v[68:69], v[2:3], 0, s[26:27]
	v_lshl_add_u64 v[4:5], s[18:19], 0, v[0:1]
	s_mov_b64 s[26:27], 0x4c00000
	v_lshlrev_b32_e32 v1, 3, v128
	s_add_i32 s6, 0, 0x16000
	v_lshl_add_u64 v[70:71], v[4:5], 0, s[26:27]
	v_and_b32_e32 v4, 0xffffffc0, v1
	s_add_i32 s4, 0, 0x17000
	v_add_u32_e32 v86, s6, v66
	v_add_u32_e32 v1, s63, v4
	s_mov_b32 s6, 0xac00
	v_lshl_add_u32 v65, v0, 2, s4
	v_cmp_gt_u32_e64 s[4:5], 8, v128
	v_mad_i64_i32 v[72:73], s[26:27], v1, s6, 0
	s_and_b64 s[24:25], s[40:41], s[4:5]
	s_mov_b64 s[26:27], 0xa0000
	v_lshl_add_u64 v[74:75], v[2:3], 0, s[26:27]
	s_add_u32 s26, s18, s63
	s_addc_u32 s27, s19, 0
	v_ashrrev_i32_e32 v5, 31, v4
	v_lshl_add_u64 v[2:3], s[26:27], 0, v[4:5]
	s_mov_b64 s[26:27], 0x6c00000
	s_lshl_b32 s6, s2, 5
	v_writelane_b32 v247, s84, 1
	v_lshl_add_u64 v[76:77], v[2:3], 0, s[26:27]
	v_or_b32_e32 v1, s6, v64
	v_mov_b32_e32 v2, 0xfe380000
	v_writelane_b32 v247, s85, 2
	v_lshl_add_u32 v78, v1, 12, v2
	v_lshl_add_u32 v0, v0, 12, v1
	v_mov_b32_e32 v1, 0xffff8e00
	v_writelane_b32 v247, s72, 3
	v_add_u32_e32 v85, s72, v66
	s_lshl_b32 s27, s64, 17
	v_lshl_add_u32 v80, v0, 2, v1
	s_lshl_b32 s38, s64, 7
	s_addk_i32 s6, 0xe380
	s_lshl_b32 s39, s64, 5
	s_mov_b32 s42, 0x204000
	s_mov_b32 s43, 0x42fe0000
	s_mov_b32 s44, 0xc0c0400
	s_mov_b32 s45, 0x5040100
	s_movk_i32 s46, 0x1000
	s_movk_i32 s47, 0x2000
	s_movk_i32 s48, 0x3000
	v_add_u32_e32 v87, 4, v65
	v_add_u32_e32 v88, 8, v65
	v_add_u32_e32 v89, 12, v65
	s_mov_b32 s49, 0xc1000
	s_mov_b32 s50, 0xcc000
	s_mov_b32 s51, 0xd7000
	s_mov_b32 s52, 0xe1000
	s_mov_b32 s53, 0xec000
	s_mov_b32 s54, 0xf7000
	s_mov_b32 s55, 0x102000
	s_mov_b32 s56, 0x10c000
	s_mov_b32 s57, 0x117000
	s_mov_b32 s58, 0x122000
	s_mov_b32 s59, 0x12d000
	s_mov_b32 s60, 0x137000
	s_mov_b32 s61, 0x142000
	s_mov_b32 s67, 0x14d000
	s_mov_b32 s69, 0x158000
	s_mov_b32 s70, 0x162000
	s_mov_b32 s71, 0x16d000
	s_mov_b32 s72, 0x178000
	s_mov_b32 s73, 0x183000
	s_mov_b32 s74, 0x18d000
	s_mov_b32 s75, 0x198000
	s_mov_b32 s76, 0x1a3000
	s_mov_b32 s77, 0x1ae000
	s_mov_b32 s78, 0x1b8000
	s_mov_b32 s79, 0x1c3000
	s_mov_b32 s80, 0x1ce000
	s_mov_b32 s81, 0x1d9000
	s_mov_b32 s82, 0x1e3000
	s_mov_b32 s83, 0x1ee000
	s_mov_b32 s84, 0x1f9000
	s_mov_b32 s85, 0x20e000
	s_mov_b32 s86, 0x219000
	s_mov_b32 s87, 0x224000
	s_mov_b32 s88, 0x22f000
	s_mov_b32 s89, 0x239000
	s_mov_b32 s90, 0x244000
	s_mov_b32 s91, 0x24f000
	s_mov_b32 s92, 0x25a000
	s_mov_b32 s93, 0x264000
	s_mov_b32 s94, 0x26f000
	s_mov_b32 s95, 0x27a000
	s_mov_b32 s96, 0x285000
	s_mov_b32 s97, 0x28f000
	s_mov_b32 s34, 0x29a000
	s_mov_b32 s35, 0x2a5000
	s_mov_b32 s62, s2
	s_mov_b32 s26, 0x3f808000
	s_branch .LBB0_22

.LBB0_21:
	s_add_i32 s62, s62, s64
	s_add_i32 s6, s6, s39
	v_add_u32_e32 v78, s27, v78
	s_cmpk_lt_i32 s62, 0x164
	v_add_u32_e32 v80, s38, v80
	s_cbranch_scc0 .LBB0_33
.LBB0_22:
	s_cmpk_gt_i32 s62, 0xe3
	s_mov_b64 s[28:29], -1
	s_cbranch_scc0 .LBB0_28
	v_mov_b32_e32 v81, v67
	v_lshl_add_u64 v[82:83], s[22:23], 0, v[80:81]
	v_add_co_u32_e32 v4, vcc, 0x200000, v82
	global_load_dwordx4 v[0:3], v80, s[22:23] nt
	s_nop 0
	v_addc_co_u32_e32 v5, vcc, 0, v83, vcc
	v_add_co_u32_e32 v8, vcc, 0x400000, v82
	global_load_dwordx4 v[4:7], v[4:5], off nt
	s_nop 0
	v_addc_co_u32_e32 v9, vcc, 0, v83, vcc
	global_load_dwordx4 v[12:15], v[8:9], off nt
	v_add_co_u32_e32 v8, vcc, 0x600000, v82
	ds_read2st64_b32 v[98:99], v65 offset0:12 offset1:14
	s_nop 0
	v_addc_co_u32_e32 v9, vcc, 0, v83, vcc
	global_load_dwordx4 v[36:39], v[8:9], off nt
	v_add_co_u32_e32 v8, vcc, 0x800000, v82
	ds_read2st64_b32 v[102:103], v65 offset0:20 offset1:22
	s_nop 0
	v_addc_co_u32_e32 v9, vcc, 0, v83, vcc
	v_add_co_u32_e32 v16, vcc, 0xa00000, v82
	global_load_dwordx4 v[8:11], v[8:9], off nt
	s_nop 0
	v_addc_co_u32_e32 v17, vcc, 0, v83, vcc
	v_add_co_u32_e32 v20, vcc, 0xc00000, v82
	global_load_dwordx4 v[16:19], v[16:17], off nt
	s_nop 0
	v_addc_co_u32_e32 v21, vcc, 0, v83, vcc
	global_load_dwordx4 v[40:43], v[20:21], off nt
	v_add_co_u32_e32 v20, vcc, 0xe00000, v82
	ds_read2st64_b32 v[92:93], v65 offset0:4 offset1:6
	s_nop 0
	v_addc_co_u32_e32 v21, vcc, 0, v83, vcc
	global_load_dwordx4 v[44:47], v[20:21], off nt
	v_add_co_u32_e32 v20, vcc, 0x1000000, v82
	s_waitcnt lgkmcnt(2)
	v_mul_f32_e32 v98, 0x3e000000, v98
	v_addc_co_u32_e32 v21, vcc, 0, v83, vcc
	v_add_co_u32_e32 v24, vcc, 0x1200000, v82
	global_load_dwordx4 v[20:23], v[20:21], off nt
	s_nop 0
	v_addc_co_u32_e32 v25, vcc, 0, v83, vcc
	v_add_co_u32_e32 v28, vcc, 0x1400000, v82
	global_load_dwordx4 v[24:27], v[24:25], off nt
	s_nop 0
	v_addc_co_u32_e32 v29, vcc, 0, v83, vcc
	global_load_dwordx4 v[48:51], v[28:29], off nt
	v_add_co_u32_e32 v28, vcc, 0x1600000, v82
	s_waitcnt lgkmcnt(1)
	v_mul_f32_e32 v102, 0x3e000000, v102
	v_addc_co_u32_e32 v29, vcc, 0, v83, vcc
	global_load_dwordx4 v[52:55], v[28:29], off nt
	v_add_co_u32_e32 v28, vcc, 0x1800000, v82
	ds_read2st64_b32 v[106:107], v65 offset0:28 offset1:30
	s_nop 0
	v_addc_co_u32_e32 v29, vcc, 0, v83, vcc
	v_add_co_u32_e32 v32, vcc, 0x1a00000, v82
	global_load_dwordx4 v[28:31], v[28:29], off nt
	s_nop 0
	v_addc_co_u32_e32 v33, vcc, 0, v83, vcc
	v_add_co_u32_e32 v56, vcc, 0x1c00000, v82
	global_load_dwordx4 v[32:35], v[32:33], off nt
	s_nop 0
	v_addc_co_u32_e32 v57, vcc, 0, v83, vcc
	v_add_co_u32_e32 v60, vcc, 0x1e00000, v82
	global_load_dwordx4 v[56:59], v[56:57], off nt
	s_nop 0
	v_addc_co_u32_e32 v61, vcc, 0, v83, vcc
	global_load_dwordx4 v[60:63], v[60:61], off nt
	s_waitcnt lgkmcnt(1)
	v_mul_f32_e32 v94, 0x3e000000, v93
	ds_read2st64_b32 v[90:91], v65 offset1:2
	s_waitcnt lgkmcnt(1)
	v_mul_f32_e32 v106, 0x3e000000, v106
	v_mul_f32_e32 v92, 0x3e000000, v92
	s_movk_i32 s28, 0x4000
	s_waitcnt lgkmcnt(0)
	v_mul_f32_e32 v66, 0x3e000000, v91
	v_mul_f32_e32 v90, 0x3e000000, v90
	s_waitcnt vmcnt(13)
	v_pk_mul_f32 v[14:15], v[14:15], v[92:93] op_sel_hi:[1,0]
	v_pk_mul_f32 v[12:13], v[12:13], v[92:93] op_sel_hi:[1,0]
	v_pk_fma_f32 v[92:93], v[2:3], v[90:91], v[14:15] op_sel_hi:[1,0,1]
	v_pk_fma_f32 v[2:3], v[2:3], v[90:91], v[14:15] op_sel_hi:[1,0,1] neg_lo:[0,0,1] neg_hi:[0,0,1]
	s_waitcnt vmcnt(12)
	v_pk_mul_f32 v[38:39], v[38:39], v[94:95] op_sel_hi:[1,0]
	v_pk_mul_f32 v[36:37], v[36:37], v[94:95] op_sel_hi:[1,0]
	ds_read2st64_b32 v[94:95], v65 offset0:8 offset1:10
	v_pk_fma_f32 v[14:15], v[4:5], v[66:67], v[36:37] op_sel_hi:[1,0,1]
	v_pk_fma_f32 v[4:5], v[4:5], v[66:67], v[36:37] op_sel_hi:[1,0,1] neg_lo:[0,0,1] neg_hi:[0,0,1]
	s_waitcnt lgkmcnt(0)
	v_mul_f32_e32 v94, 0x3e000000, v94
	v_mul_f32_e32 v96, 0x3e000000, v95
	s_waitcnt vmcnt(9)
	v_pk_mul_f32 v[42:43], v[42:43], v[98:99] op_sel_hi:[1,0]
	v_pk_mul_f32 v[40:41], v[40:41], v[98:99] op_sel_hi:[1,0]
	v_mul_f32_e32 v98, 0x3e000000, v99
	v_pk_fma_f32 v[36:37], v[10:11], v[94:95], v[42:43] op_sel_hi:[1,0,1]
	v_pk_fma_f32 v[10:11], v[10:11], v[94:95], v[42:43] op_sel_hi:[1,0,1] neg_lo:[0,0,1] neg_hi:[0,0,1]
	s_waitcnt vmcnt(8)
	v_pk_mul_f32 v[46:47], v[46:47], v[98:99] op_sel_hi:[1,0]
	v_pk_mul_f32 v[44:45], v[44:45], v[98:99] op_sel_hi:[1,0]
	ds_read2st64_b32 v[98:99], v65 offset0:16 offset1:18
	v_pk_fma_f32 v[42:43], v[16:17], v[96:97], v[44:45] op_sel_hi:[1,0,1]
	v_pk_fma_f32 v[16:17], v[16:17], v[96:97], v[44:45] op_sel_hi:[1,0,1] neg_lo:[0,0,1] neg_hi:[0,0,1]
	s_waitcnt lgkmcnt(0)
	v_mul_f32_e32 v98, 0x3e000000, v98
	v_mul_f32_e32 v100, 0x3e000000, v99
	s_waitcnt vmcnt(5)
	v_pk_mul_f32 v[50:51], v[50:51], v[102:103] op_sel_hi:[1,0]
	v_pk_mul_f32 v[48:49], v[48:49], v[102:103] op_sel_hi:[1,0]
	v_mul_f32_e32 v102, 0x3e000000, v103
	v_pk_fma_f32 v[44:45], v[22:23], v[98:99], v[50:51] op_sel_hi:[1,0,1]
	v_pk_fma_f32 v[22:23], v[22:23], v[98:99], v[50:51] op_sel_hi:[1,0,1] neg_lo:[0,0,1] neg_hi:[0,0,1]
	s_waitcnt vmcnt(4)
	v_pk_mul_f32 v[54:55], v[54:55], v[102:103] op_sel_hi:[1,0]
	v_pk_mul_f32 v[52:53], v[52:53], v[102:103] op_sel_hi:[1,0]
	ds_read2st64_b32 v[102:103], v65 offset0:24 offset1:26
	v_pk_fma_f32 v[50:51], v[24:25], v[100:101], v[52:53] op_sel_hi:[1,0,1]
	v_pk_fma_f32 v[24:25], v[24:25], v[100:101], v[52:53] op_sel_hi:[1,0,1] neg_lo:[0,0,1] neg_hi:[0,0,1]
	s_waitcnt lgkmcnt(0)
	v_mul_f32_e32 v102, 0x3e000000, v102
	v_mul_f32_e32 v104, 0x3e000000, v103
	s_waitcnt vmcnt(1)
	v_pk_mul_f32 v[58:59], v[58:59], v[106:107] op_sel_hi:[1,0]
	v_pk_mul_f32 v[56:57], v[56:57], v[106:107] op_sel_hi:[1,0]
	v_mul_f32_e32 v106, 0x3e000000, v107
	s_waitcnt vmcnt(0)
	v_pk_mul_f32 v[60:61], v[60:61], v[106:107] op_sel_hi:[1,0]
	v_pk_mul_f32 v[62:63], v[62:63], v[106:107] op_sel_hi:[1,0]
	v_pk_fma_f32 v[106:107], v[0:1], v[90:91], v[12:13] op_sel_hi:[1,0,1]
	v_pk_fma_f32 v[0:1], v[0:1], v[90:91], v[12:13] op_sel_hi:[1,0,1] neg_lo:[0,0,1] neg_hi:[0,0,1]
	v_pk_fma_f32 v[12:13], v[6:7], v[66:67], v[38:39] op_sel_hi:[1,0,1]
	v_pk_fma_f32 v[6:7], v[6:7], v[66:67], v[38:39] op_sel_hi:[1,0,1] neg_lo:[0,0,1] neg_hi:[0,0,1]
	v_pk_fma_f32 v[38:39], v[8:9], v[94:95], v[40:41] op_sel_hi:[1,0,1]
	v_pk_fma_f32 v[8:9], v[8:9], v[94:95], v[40:41] op_sel_hi:[1,0,1] neg_lo:[0,0,1] neg_hi:[0,0,1]
	v_pk_fma_f32 v[40:41], v[18:19], v[96:97], v[46:47] op_sel_hi:[1,0,1]
	v_pk_fma_f32 v[18:19], v[18:19], v[96:97], v[46:47] op_sel_hi:[1,0,1] neg_lo:[0,0,1] neg_hi:[0,0,1]
	v_pk_fma_f32 v[46:47], v[20:21], v[98:99], v[48:49] op_sel_hi:[1,0,1]
	v_pk_fma_f32 v[20:21], v[20:21], v[98:99], v[48:49] op_sel_hi:[1,0,1] neg_lo:[0,0,1] neg_hi:[0,0,1]
	v_pk_fma_f32 v[48:49], v[26:27], v[100:101], v[54:55] op_sel_hi:[1,0,1]
	v_pk_fma_f32 v[26:27], v[26:27], v[100:101], v[54:55] op_sel_hi:[1,0,1] neg_lo:[0,0,1] neg_hi:[0,0,1]
	v_pk_fma_f32 v[52:53], v[30:31], v[102:103], v[58:59] op_sel_hi:[1,0,1]
	v_pk_fma_f32 v[54:55], v[28:29], v[102:103], v[56:57] op_sel_hi:[1,0,1]
	v_pk_fma_f32 v[30:31], v[30:31], v[102:103], v[58:59] op_sel_hi:[1,0,1] neg_lo:[0,0,1] neg_hi:[0,0,1]
	v_pk_fma_f32 v[58:59], v[32:33], v[104:105], v[60:61] op_sel_hi:[1,0,1]
	v_pk_fma_f32 v[28:29], v[28:29], v[102:103], v[56:57] op_sel_hi:[1,0,1] neg_lo:[0,0,1] neg_hi:[0,0,1]
	v_pk_fma_f32 v[56:57], v[34:35], v[104:105], v[62:63] op_sel_hi:[1,0,1]
	v_pk_fma_f32 v[34:35], v[34:35], v[104:105], v[62:63] op_sel_hi:[1,0,1] neg_lo:[0,0,1] neg_hi:[0,0,1]
	v_pk_fma_f32 v[32:33], v[32:33], v[104:105], v[60:61] op_sel_hi:[1,0,1] neg_lo:[0,0,1] neg_hi:[0,0,1]
	v_pk_add_f32 v[60:61], v[92:93], v[36:37]
	v_pk_add_f32 v[62:63], v[106:107], v[38:39]
	v_sub_f32_e32 v37, v93, v37
	v_sub_f32_e32 v36, v92, v36
	v_pk_add_f32 v[92:93], v[14:15], v[42:43]
	v_sub_f32_e32 v15, v15, v43
	v_sub_f32_e32 v14, v14, v42
	v_pk_add_f32 v[42:43], v[0:1], v[8:9]
	v_sub_f32_e32 v1, v1, v9
	v_sub_f32_e32 v0, v0, v8
	v_pk_add_f32 v[8:9], v[6:7], v[18:19]
	v_sub_f32_e32 v7, v7, v19
	v_sub_f32_e32 v6, v6, v18
	v_pk_add_f32 v[18:19], v[46:47], v[54:55]
	v_sub_f32_e32 v47, v47, v55
	v_sub_f32_e32 v46, v46, v54
	v_pk_add_f32 v[54:55], v[50:51], v[58:59]
	v_pk_add_f32 v[90:91], v[12:13], v[40:41]
	v_sub_f32_e32 v13, v13, v41
	v_sub_f32_e32 v12, v12, v40
	v_pk_add_f32 v[40:41], v[2:3], v[10:11]
	v_sub_f32_e32 v3, v3, v11
	v_sub_f32_e32 v2, v2, v10
	v_pk_add_f32 v[10:11], v[4:5], v[16:17]
	v_sub_f32_e32 v5, v5, v17
	v_sub_f32_e32 v4, v4, v16
	v_pk_add_f32 v[16:17], v[44:45], v[52:53]
	v_sub_f32_e32 v45, v45, v53
	v_sub_f32_e32 v44, v44, v52
	v_pk_add_f32 v[52:53], v[48:49], v[56:57]
	v_sub_f32_e32 v49, v49, v57
	v_sub_f32_e32 v48, v48, v56
	v_sub_f32_e32 v51, v51, v59
	v_sub_f32_e32 v50, v50, v58
	v_pk_add_f32 v[56:57], v[22:23], v[30:31]
	v_pk_add_f32 v[58:59], v[20:21], v[28:29]
	v_sub_f32_e32 v23, v23, v31
	v_sub_f32_e32 v22, v22, v30
	v_sub_f32_e32 v21, v21, v29
	v_sub_f32_e32 v20, v20, v28
	v_pk_add_f32 v[28:29], v[26:27], v[34:35]
	v_pk_add_f32 v[30:31], v[24:25], v[32:33]
	v_sub_f32_e32 v27, v27, v35
	v_sub_f32_e32 v26, v26, v34
	v_sub_f32_e32 v25, v25, v33
	v_sub_f32_e32 v24, v24, v32
	v_pk_add_f32 v[34:35], v[62:63], v[18:19]
	v_sub_f32_e32 v62, v62, v18
	v_sub_f32_e32 v63, v63, v19
	v_pk_add_f32 v[18:19], v[92:93], v[54:55]
	v_sub_f32_e32 v39, v107, v39
	v_sub_f32_e32 v38, v106, v38
	v_pk_add_f32 v[32:33], v[60:61], v[16:17]
	v_sub_f32_e32 v60, v60, v16
	v_sub_f32_e32 v61, v61, v17
	v_pk_add_f32 v[16:17], v[90:91], v[52:53]
	v_sub_f32_e32 v66, v91, v53
	v_sub_f32_e32 v79, v90, v52
	v_sub_f32_e32 v81, v93, v55
	v_sub_f32_e32 v90, v92, v54
	v_pk_add_f32 v[52:53], v[40:41], v[56:57]
	v_pk_add_f32 v[54:55], v[42:43], v[58:59]
	v_sub_f32_e32 v56, v40, v56
	v_sub_f32_e32 v57, v41, v57
	v_sub_f32_e32 v58, v42, v58
	v_sub_f32_e32 v59, v43, v59
	v_pk_add_f32 v[40:41], v[8:9], v[28:29]
	v_pk_add_f32 v[42:43], v[10:11], v[30:31]
	v_sub_f32_e32 v92, v9, v29
	v_sub_f32_e32 v93, v8, v28
	v_pk_add_f32 v[8:9], v[36:37], v[44:45]
	v_sub_f32_e32 v36, v36, v44
	v_sub_f32_e32 v37, v37, v45
	v_pk_add_f32 v[28:29], v[12:13], v[48:49]
	v_sub_f32_e32 v44, v13, v49
	v_sub_f32_e32 v45, v12, v48
	v_pk_add_f32 v[12:13], v[2:3], v[22:23]
	v_sub_f32_e32 v22, v2, v22
	v_sub_f32_e32 v23, v3, v23
	v_pk_add_f32 v[2:3], v[4:5], v[24:25]
	v_sub_f32_e32 v4, v4, v24
	v_max3_f32 v24, |v34|, 0, |v18|
	v_sub_f32_e32 v104, v11, v31
	v_sub_f32_e32 v105, v10, v30
	v_pk_add_f32 v[10:11], v[38:39], v[46:47]
	v_sub_f32_e32 v38, v38, v46
	v_sub_f32_e32 v39, v39, v47
	v_pk_add_f32 v[30:31], v[14:15], v[50:51]
	v_sub_f32_e32 v46, v15, v51
	v_sub_f32_e32 v47, v14, v50
	v_pk_add_f32 v[14:15], v[0:1], v[20:21]
	v_sub_f32_e32 v20, v0, v20
	v_sub_f32_e32 v21, v1, v21
	v_pk_add_f32 v[0:1], v[6:7], v[26:27]
	v_sub_f32_e32 v6, v6, v26
	v_sub_f32_e32 v5, v5, v25
	v_cvt_pk_bf16_f32 v119, v34, v35
	v_cvt_pk_bf16_f32 v103, v32, v33
	v_max3_f32 v25, |v35|, 0, |v19|
	v_max3_f32 v26, |v32|, 0, |v16|
	v_cvt_pk_bf16_f32 v118, v18, v19
	v_cvt_pk_bf16_f32 v102, v16, v17
	v_max3_f32 v16, v24, |v54|, |v42|
	v_sub_f32_e32 v7, v7, v27
	v_max3_f32 v27, |v33|, 0, |v17|
	v_cvt_pk_bf16_f32 v117, v54, v55
	v_cvt_pk_bf16_f32 v101, v52, v53
	v_max3_f32 v17, v25, |v55|, |v43|
	v_max3_f32 v18, v26, |v52|, |v40|
	v_cvt_pk_bf16_f32 v116, v42, v43
	v_cvt_pk_bf16_f32 v100, v40, v41
	v_cvt_pk_bf16_f32 v115, v10, v11
	v_max3_f32 v10, v16, |v10|, |v30|
	v_max3_f32 v19, v27, |v53|, |v41|
	v_cvt_pk_bf16_f32 v99, v8, v9
	v_max3_f32 v11, v17, |v11|, |v31|
	v_max3_f32 v8, v18, |v8|, |v28|
	v_max3_f32 v10, v10, |v14|, |v2|
	v_max3_f32 v9, v19, |v9|, |v29|
	v_cvt_pk_bf16_f32 v114, v30, v31
	v_cvt_pk_bf16_f32 v98, v28, v29
	v_cvt_pk_bf16_f32 v113, v14, v15
	v_cvt_pk_bf16_f32 v97, v12, v13
	v_max3_f32 v11, v11, |v15|, |v3|
	v_max3_f32 v8, v8, |v12|, |v0|
	v_cvt_pk_bf16_f32 v112, v2, v3
	v_cvt_pk_bf16_f32 v96, v0, v1
	v_max3_f32 v0, v10, |v62|, |v90|
	v_max3_f32 v9, v9, |v13|, |v1|
	v_max3_f32 v1, v11, |v63|, |v81|
	v_max3_f32 v0, v0, |v58|, |v105|
	v_max3_f32 v2, v8, |v60|, |v79|
	v_max3_f32 v3, v9, |v61|, |v66|
	v_max3_f32 v1, v1, |v59|, |v104|
	v_max3_f32 v0, v0, |v38|, |v47|
	v_max3_f32 v2, v2, |v56|, |v93|
	v_max3_f32 v3, v3, |v57|, |v92|
	v_max3_f32 v1, v1, |v39|, |v46|
	v_max3_f32 v122, v0, |v20|, |v4|
	v_add_co_u32_e32 v0, vcc, s28, v82
	v_max3_f32 v2, v2, |v36|, |v45|
	v_max3_f32 v3, v3, |v37|, |v44|
	v_max3_f32 v121, v1, |v21|, |v5|
	v_addc_co_u32_e32 v1, vcc, 0, v83, vcc
	v_cvt_pk_bf16_f32 v111, v62, v63
	v_cvt_pk_bf16_f32 v95, v60, v61
	v_cvt_pk_bf16_f32 v110, v90, v81
	v_cvt_pk_bf16_f32 v94, v79, v66
	v_cvt_pk_bf16_f32 v106, v58, v59
	v_cvt_pk_bf16_f32 v91, v56, v57
	v_cvt_pk_bf16_f32 v107, v105, v104
	v_cvt_pk_bf16_f32 v92, v93, v92
	v_cvt_pk_bf16_f32 v104, v38, v39
	v_cvt_pk_bf16_f32 v66, v36, v37
	v_cvt_pk_bf16_f32 v108, v47, v46
	v_cvt_pk_bf16_f32 v93, v45, v44
	v_cvt_pk_bf16_f32 v105, v20, v21
	v_cvt_pk_bf16_f32 v81, v22, v23
	v_max3_f32 v120, v2, |v22|, |v6|
	v_max3_f32 v79, v3, |v23|, |v7|
	v_cvt_pk_bf16_f32 v109, v4, v5
	v_cvt_pk_bf16_f32 v90, v6, v7
	global_load_dwordx4 v[4:7], v[0:1], off nt
	v_add_co_u32_e32 v0, vcc, s42, v82
	s_mov_b32 s28, 0x404000
	s_nop 0
	v_addc_co_u32_e32 v1, vcc, 0, v83, vcc
	v_add_co_u32_e32 v8, vcc, s28, v82
	s_mov_b32 s28, 0x604000
	s_nop 0
	v_addc_co_u32_e32 v9, vcc, 0, v83, vcc
	v_add_co_u32_e32 v12, vcc, s28, v82
	s_mov_b32 s28, 0x804000
	s_nop 0
	v_addc_co_u32_e32 v13, vcc, 0, v83, vcc
	global_load_dwordx4 v[60:63], v[12:13], off nt
	v_add_co_u32_e32 v12, vcc, s28, v82
	s_mov_b32 s28, 0xa04000
	s_nop 0
	v_addc_co_u32_e32 v13, vcc, 0, v83, vcc
	global_load_dwordx4 v[16:19], v[12:13], off nt
	v_add_co_u32_e32 v12, vcc, s28, v82
	s_mov_b32 s28, 0xc04000
	s_nop 0
	v_addc_co_u32_e32 v13, vcc, 0, v83, vcc
	v_add_co_u32_e32 v20, vcc, s28, v82
	s_mov_b32 s28, 0xe04000
	s_nop 0
	v_addc_co_u32_e32 v21, vcc, 0, v83, vcc
	global_load_dwordx4 v[12:15], v[12:13], off nt
	ds_read2st64_b32 v[136:137], v87 offset0:12 offset1:14
	global_load_dwordx4 v[48:51], v[20:21], off nt
	v_add_co_u32_e32 v20, vcc, s28, v82
	s_mov_b32 s28, 0x1004000
	s_nop 0
	v_addc_co_u32_e32 v21, vcc, 0, v83, vcc
	global_load_dwordx4 v[56:59], v[20:21], off nt
	v_add_co_u32_e32 v20, vcc, s28, v82
	s_mov_b32 s28, 0x1204000
	s_nop 0
	v_addc_co_u32_e32 v21, vcc, 0, v83, vcc
	global_load_dwordx4 v[24:27], v[20:21], off nt
	v_add_co_u32_e32 v20, vcc, s28, v82
	s_mov_b32 s28, 0x1404000
	s_nop 0
	v_addc_co_u32_e32 v21, vcc, 0, v83, vcc
	v_add_co_u32_e32 v28, vcc, s28, v82
	s_mov_b32 s28, 0x1604000
	s_nop 0
	v_addc_co_u32_e32 v29, vcc, 0, v83, vcc
	global_load_dwordx4 v[20:23], v[20:21], off nt
	ds_read2st64_b32 v[140:141], v87 offset0:20 offset1:22
	global_load_dwordx4 v[44:47], v[28:29], off nt
	v_add_co_u32_e32 v28, vcc, s28, v82
	s_mov_b32 s28, 0x1804000
	s_nop 0
	v_addc_co_u32_e32 v29, vcc, 0, v83, vcc
	global_load_dwordx4 v[52:55], v[28:29], off nt
	v_add_co_u32_e32 v28, vcc, s28, v82
	s_mov_b32 s28, 0x1a04000
	s_nop 0
	v_addc_co_u32_e32 v29, vcc, 0, v83, vcc
	global_load_dwordx4 v[32:35], v[28:29], off nt
	v_add_co_u32_e32 v28, vcc, s28, v82
	s_mov_b32 s28, 0x1c04000
	s_nop 0
	v_addc_co_u32_e32 v29, vcc, 0, v83, vcc
	v_add_co_u32_e32 v36, vcc, s28, v82
	s_mov_b32 s28, 0x1e04000
	s_nop 0
	v_addc_co_u32_e32 v37, vcc, 0, v83, vcc
	v_add_co_u32_e32 v40, vcc, s28, v82
	global_load_dwordx4 v[28:31], v[28:29], off nt
	s_nop 0
	v_addc_co_u32_e32 v41, vcc, 0, v83, vcc
	global_load_dwordx4 v[36:39], v[36:37], off nt
	ds_read2st64_b32 v[130:131], v87 offset0:4 offset1:6
	global_load_dwordx4 v[0:3], v[0:1], off nt
	s_waitcnt lgkmcnt(2)
	v_mul_f32_e32 v136, 0x3e000000, v136
	global_load_dwordx4 v[8:11], v[8:9], off nt
	s_waitcnt lgkmcnt(1)
	v_mul_f32_e32 v140, 0x3e000000, v140
	global_load_dwordx4 v[40:43], v[40:41], off nt
	ds_read2st64_b32 v[144:145], v87 offset0:28 offset1:30
	s_waitcnt lgkmcnt(1)
	v_mul_f32_e32 v132, 0x3e000000, v131
	ds_read2_b32 v[124:125], v65 offset0:1 offset1:129
	s_waitcnt vmcnt(14)
	v_pk_mul_f32 v[62:63], v[62:63], v[132:133] op_sel_hi:[1,0]
	v_pk_mul_f32 v[60:61], v[60:61], v[132:133] op_sel_hi:[1,0]
	ds_read2st64_b32 v[132:133], v87 offset0:8 offset1:10
	s_waitcnt lgkmcnt(2)
	v_mul_f32_e32 v144, 0x3e000000, v144
	v_mul_f32_e32 v130, 0x3e000000, v130
	s_waitcnt lgkmcnt(1)
	v_mul_f32_e32 v126, 0x3e000000, v125
	v_mul_f32_e32 v124, 0x3e000000, v124
	s_waitcnt lgkmcnt(0)
	v_mul_f32_e32 v132, 0x3e000000, v132
	v_mul_f32_e32 v134, 0x3e000000, v133
	s_mov_b32 s28, 0x8000
	s_waitcnt vmcnt(11)
	v_pk_mul_f32 v[50:51], v[50:51], v[136:137] op_sel_hi:[1,0]
	v_pk_mul_f32 v[48:49], v[48:49], v[136:137] op_sel_hi:[1,0]
	v_mul_f32_e32 v136, 0x3e000000, v137
	s_waitcnt vmcnt(10)
	v_pk_mul_f32 v[58:59], v[58:59], v[136:137] op_sel_hi:[1,0]
	v_pk_mul_f32 v[56:57], v[56:57], v[136:137] op_sel_hi:[1,0]
	ds_read2st64_b32 v[136:137], v87 offset0:16 offset1:18
	s_waitcnt lgkmcnt(0)
	v_mul_f32_e32 v136, 0x3e000000, v136
	v_mul_f32_e32 v138, 0x3e000000, v137
	s_waitcnt vmcnt(7)
	v_pk_mul_f32 v[46:47], v[46:47], v[140:141] op_sel_hi:[1,0]
	v_pk_mul_f32 v[44:45], v[44:45], v[140:141] op_sel_hi:[1,0]
	v_mul_f32_e32 v140, 0x3e000000, v141
	s_waitcnt vmcnt(6)
	v_pk_mul_f32 v[54:55], v[54:55], v[140:141] op_sel_hi:[1,0]
	v_pk_mul_f32 v[52:53], v[52:53], v[140:141] op_sel_hi:[1,0]
	ds_read2st64_b32 v[140:141], v87 offset0:24 offset1:26
	s_waitcnt lgkmcnt(0)
	v_mul_f32_e32 v140, 0x3e000000, v140
	v_mul_f32_e32 v142, 0x3e000000, v141
	s_waitcnt vmcnt(3)
	v_pk_mul_f32 v[38:39], v[38:39], v[144:145] op_sel_hi:[1,0]
	v_pk_mul_f32 v[36:37], v[36:37], v[144:145] op_sel_hi:[1,0]
	v_mul_f32_e32 v144, 0x3e000000, v145
	s_waitcnt vmcnt(1)
	v_pk_mul_f32 v[10:11], v[10:11], v[130:131] op_sel_hi:[1,0]
	v_pk_mul_f32 v[8:9], v[8:9], v[130:131] op_sel_hi:[1,0]
	s_waitcnt vmcnt(0)
	v_pk_mul_f32 v[40:41], v[40:41], v[144:145] op_sel_hi:[1,0]
	v_pk_mul_f32 v[42:43], v[42:43], v[144:145] op_sel_hi:[1,0]
	v_pk_fma_f32 v[130:131], v[6:7], v[124:125], v[10:11] op_sel_hi:[1,0,1]
	v_pk_fma_f32 v[144:145], v[4:5], v[124:125], v[8:9] op_sel_hi:[1,0,1]
	v_pk_fma_f32 v[6:7], v[6:7], v[124:125], v[10:11] op_sel_hi:[1,0,1] neg_lo:[0,0,1] neg_hi:[0,0,1]
	v_pk_fma_f32 v[4:5], v[4:5], v[124:125], v[8:9] op_sel_hi:[1,0,1] neg_lo:[0,0,1] neg_hi:[0,0,1]
	v_pk_fma_f32 v[8:9], v[2:3], v[126:127], v[62:63] op_sel_hi:[1,0,1]
	v_pk_fma_f32 v[10:11], v[0:1], v[126:127], v[60:61] op_sel_hi:[1,0,1]
	v_pk_fma_f32 v[2:3], v[2:3], v[126:127], v[62:63] op_sel_hi:[1,0,1] neg_lo:[0,0,1] neg_hi:[0,0,1]
	v_pk_fma_f32 v[0:1], v[0:1], v[126:127], v[60:61] op_sel_hi:[1,0,1] neg_lo:[0,0,1] neg_hi:[0,0,1]
	v_pk_fma_f32 v[60:61], v[18:19], v[132:133], v[50:51] op_sel_hi:[1,0,1]
	v_pk_fma_f32 v[62:63], v[16:17], v[132:133], v[48:49] op_sel_hi:[1,0,1]
	v_pk_fma_f32 v[18:19], v[18:19], v[132:133], v[50:51] op_sel_hi:[1,0,1] neg_lo:[0,0,1] neg_hi:[0,0,1]
	v_pk_fma_f32 v[16:17], v[16:17], v[132:133], v[48:49] op_sel_hi:[1,0,1] neg_lo:[0,0,1] neg_hi:[0,0,1]
	v_pk_fma_f32 v[48:49], v[14:15], v[134:135], v[58:59] op_sel_hi:[1,0,1]
	v_pk_fma_f32 v[50:51], v[12:13], v[134:135], v[56:57] op_sel_hi:[1,0,1]
	v_pk_fma_f32 v[14:15], v[14:15], v[134:135], v[58:59] op_sel_hi:[1,0,1] neg_lo:[0,0,1] neg_hi:[0,0,1]
	v_pk_fma_f32 v[12:13], v[12:13], v[134:135], v[56:57] op_sel_hi:[1,0,1] neg_lo:[0,0,1] neg_hi:[0,0,1]
	v_pk_fma_f32 v[56:57], v[26:27], v[136:137], v[46:47] op_sel_hi:[1,0,1]
	v_pk_fma_f32 v[58:59], v[24:25], v[136:137], v[44:45] op_sel_hi:[1,0,1]
	v_pk_fma_f32 v[26:27], v[26:27], v[136:137], v[46:47] op_sel_hi:[1,0,1] neg_lo:[0,0,1] neg_hi:[0,0,1]
	v_pk_fma_f32 v[24:25], v[24:25], v[136:137], v[44:45] op_sel_hi:[1,0,1] neg_lo:[0,0,1] neg_hi:[0,0,1]
	v_pk_fma_f32 v[44:45], v[22:23], v[138:139], v[54:55] op_sel_hi:[1,0,1]
	v_pk_fma_f32 v[46:47], v[20:21], v[138:139], v[52:53] op_sel_hi:[1,0,1]
	v_pk_fma_f32 v[22:23], v[22:23], v[138:139], v[54:55] op_sel_hi:[1,0,1] neg_lo:[0,0,1] neg_hi:[0,0,1]
	v_pk_fma_f32 v[20:21], v[20:21], v[138:139], v[52:53] op_sel_hi:[1,0,1] neg_lo:[0,0,1] neg_hi:[0,0,1]
	v_pk_fma_f32 v[52:53], v[34:35], v[140:141], v[38:39] op_sel_hi:[1,0,1]
	v_pk_fma_f32 v[54:55], v[32:33], v[140:141], v[36:37] op_sel_hi:[1,0,1]
	v_pk_fma_f32 v[34:35], v[34:35], v[140:141], v[38:39] op_sel_hi:[1,0,1] neg_lo:[0,0,1] neg_hi:[0,0,1]
	v_pk_fma_f32 v[38:39], v[28:29], v[142:143], v[40:41] op_sel_hi:[1,0,1]
	v_pk_fma_f32 v[32:33], v[32:33], v[140:141], v[36:37] op_sel_hi:[1,0,1] neg_lo:[0,0,1] neg_hi:[0,0,1]
	v_pk_fma_f32 v[36:37], v[30:31], v[142:143], v[42:43] op_sel_hi:[1,0,1]
	v_pk_fma_f32 v[30:31], v[30:31], v[142:143], v[42:43] op_sel_hi:[1,0,1] neg_lo:[0,0,1] neg_hi:[0,0,1]
	v_pk_fma_f32 v[28:29], v[28:29], v[142:143], v[40:41] op_sel_hi:[1,0,1] neg_lo:[0,0,1] neg_hi:[0,0,1]
	v_pk_add_f32 v[42:43], v[144:145], v[62:63]
	v_pk_add_f32 v[126:127], v[10:11], v[50:51]
	v_sub_f32_e32 v11, v11, v51
	v_sub_f32_e32 v10, v10, v50
	v_pk_add_f32 v[50:51], v[4:5], v[16:17]
	v_sub_f32_e32 v5, v5, v17
	v_sub_f32_e32 v4, v4, v16
	v_pk_add_f32 v[16:17], v[2:3], v[14:15]
	v_sub_f32_e32 v3, v3, v15
	v_sub_f32_e32 v2, v2, v14
	v_pk_add_f32 v[14:15], v[58:59], v[54:55]
	v_sub_f32_e32 v55, v59, v55
	v_sub_f32_e32 v54, v58, v54
	v_pk_add_f32 v[58:59], v[46:47], v[38:39]
	v_pk_add_f32 v[40:41], v[130:131], v[60:61]
	v_pk_add_f32 v[124:125], v[8:9], v[48:49]
	v_sub_f32_e32 v9, v9, v49
	v_sub_f32_e32 v8, v8, v48
	v_pk_add_f32 v[48:49], v[6:7], v[18:19]
	v_sub_f32_e32 v7, v7, v19
	v_sub_f32_e32 v6, v6, v18
	v_pk_add_f32 v[18:19], v[0:1], v[12:13]
	v_sub_f32_e32 v1, v1, v13
	v_sub_f32_e32 v0, v0, v12
	v_pk_add_f32 v[12:13], v[56:57], v[52:53]
	v_sub_f32_e32 v53, v57, v53
	v_sub_f32_e32 v52, v56, v52
	v_pk_add_f32 v[56:57], v[44:45], v[36:37]
	v_sub_f32_e32 v37, v45, v37
	v_sub_f32_e32 v36, v44, v36
	v_sub_f32_e32 v39, v47, v39
	v_sub_f32_e32 v38, v46, v38
	v_pk_add_f32 v[44:45], v[26:27], v[34:35]
	v_pk_add_f32 v[46:47], v[24:25], v[32:33]
	v_sub_f32_e32 v27, v27, v35
	v_sub_f32_e32 v26, v26, v34
	v_sub_f32_e32 v25, v25, v33
	v_sub_f32_e32 v24, v24, v32
	v_pk_add_f32 v[32:33], v[22:23], v[30:31]
	v_pk_add_f32 v[34:35], v[20:21], v[28:29]
	v_sub_f32_e32 v23, v23, v31
	v_sub_f32_e32 v22, v22, v30
	v_sub_f32_e32 v21, v21, v29
	v_sub_f32_e32 v20, v20, v28
	v_pk_add_f32 v[30:31], v[42:43], v[14:15]
	v_sub_f32_e32 v138, v42, v14
	v_sub_f32_e32 v139, v43, v15
	v_pk_add_f32 v[14:15], v[126:127], v[58:59]
	v_sub_f32_e32 v63, v145, v63
	v_sub_f32_e32 v62, v144, v62
	v_pk_add_f32 v[28:29], v[40:41], v[12:13]
	v_sub_f32_e32 v123, v40, v12
	v_sub_f32_e32 v137, v41, v13
	v_pk_add_f32 v[12:13], v[124:125], v[56:57]
	v_sub_f32_e32 v57, v125, v57
	v_sub_f32_e32 v56, v124, v56
	v_pk_add_f32 v[40:41], v[48:49], v[44:45]
	v_pk_add_f32 v[42:43], v[50:51], v[46:47]
	v_sub_f32_e32 v48, v48, v44
	v_sub_f32_e32 v49, v49, v45
	v_sub_f32_e32 v50, v50, v46
	v_sub_f32_e32 v51, v51, v47
	v_pk_add_f32 v[44:45], v[16:17], v[32:33]
	v_pk_add_f32 v[46:47], v[18:19], v[34:35]
	v_sub_f32_e32 v124, v17, v33
	v_sub_f32_e32 v125, v16, v32
	v_pk_add_f32 v[32:33], v[8:9], v[36:37]
	v_sub_f32_e32 v37, v9, v37
	v_sub_f32_e32 v36, v8, v36
	v_pk_add_f32 v[8:9], v[6:7], v[26:27]
	v_sub_f32_e32 v26, v6, v26
	v_sub_f32_e32 v27, v7, v27
	v_pk_add_f32 v[6:7], v[0:1], v[20:21]
	v_sub_f32_e32 v0, v0, v20
	v_max3_f32 v20, v122, |v30|, |v14|
	v_sub_f32_e32 v61, v131, v61
	v_sub_f32_e32 v60, v130, v60
	v_sub_f32_e32 v140, v19, v35
	v_sub_f32_e32 v141, v18, v34
	v_pk_add_f32 v[18:19], v[62:63], v[54:55]
	v_pk_add_f32 v[34:35], v[10:11], v[38:39]
	v_sub_f32_e32 v39, v11, v39
	v_sub_f32_e32 v38, v10, v38
	v_pk_add_f32 v[10:11], v[4:5], v[24:25]
	v_sub_f32_e32 v24, v4, v24
	v_sub_f32_e32 v25, v5, v25
	v_pk_add_f32 v[4:5], v[2:3], v[22:23]
	v_sub_f32_e32 v2, v2, v22
	v_sub_f32_e32 v1, v1, v21
	v_cvt_pk_bf16_f32 v152, v30, v31
	v_cvt_pk_bf16_f32 v136, v28, v29
	v_max3_f32 v21, v121, |v31|, |v15|
	v_max3_f32 v22, v120, |v28|, |v12|
	v_cvt_pk_bf16_f32 v151, v14, v15
	v_cvt_pk_bf16_f32 v135, v12, v13
	v_max3_f32 v12, v20, |v42|, |v46|
	v_pk_add_f32 v[16:17], v[60:61], v[52:53]
	v_sub_f32_e32 v3, v3, v23
	v_max3_f32 v23, v79, |v29|, |v13|
	v_max3_f32 v13, v21, |v43|, |v47|
	v_max3_f32 v14, v22, |v40|, |v44|
	v_max3_f32 v12, v12, |v18|, |v34|
	v_sub_f32_e32 v58, v126, v58
	v_cvt_pk_bf16_f32 v150, v42, v43
	v_cvt_pk_bf16_f32 v134, v40, v41
	v_max3_f32 v15, v23, |v41|, |v45|
	v_cvt_pk_bf16_f32 v149, v46, v47
	v_cvt_pk_bf16_f32 v133, v44, v45
	v_cvt_pk_bf16_f32 v148, v18, v19
	v_cvt_pk_bf16_f32 v132, v16, v17
	v_max3_f32 v13, v13, |v19|, |v35|
	v_max3_f32 v14, v14, |v16|, |v32|
	v_cvt_pk_bf16_f32 v147, v34, v35
	v_cvt_pk_bf16_f32 v131, v32, v33
	v_cvt_pk_bf16_f32 v146, v10, v11
	v_max3_f32 v10, v12, |v10|, |v6|
	v_sub_f32_e32 v59, v127, v59
	v_max3_f32 v15, v15, |v17|, |v33|
	v_cvt_pk_bf16_f32 v130, v8, v9
	v_max3_f32 v11, v13, |v11|, |v7|
	v_max3_f32 v8, v14, |v8|, |v4|
	v_cvt_pk_bf16_f32 v145, v6, v7
	v_cvt_pk_bf16_f32 v129, v4, v5
	v_max3_f32 v4, v10, |v138|, |v58|
	v_sub_f32_e32 v54, v62, v54
	v_max3_f32 v9, v15, |v9|, |v5|
	v_max3_f32 v5, v11, |v139|, |v59|
	v_max3_f32 v4, v4, |v50|, |v141|
	v_sub_f32_e32 v55, v63, v55
	v_max3_f32 v6, v8, |v123|, |v56|
	v_max3_f32 v7, v9, |v137|, |v57|
	v_max3_f32 v5, v5, |v51|, |v140|
	v_max3_f32 v4, v4, |v54|, |v38|
	v_sub_f32_e32 v52, v60, v52
	v_sub_f32_e32 v53, v61, v53
	v_cvt_pk_bf16_f32 v144, v138, v139
	v_cvt_pk_bf16_f32 v127, v123, v137
	v_cvt_pk_bf16_f32 v143, v58, v59
	v_cvt_pk_bf16_f32 v126, v56, v57
	v_cvt_pk_bf16_f32 v139, v50, v51
	v_cvt_pk_bf16_f32 v122, v48, v49
	v_max3_f32 v6, v6, |v48|, |v125|
	v_max3_f32 v7, v7, |v49|, |v124|
	v_cvt_pk_bf16_f32 v140, v141, v140
	v_cvt_pk_bf16_f32 v124, v125, v124
	v_cvt_pk_bf16_f32 v137, v54, v55
	v_cvt_pk_bf16_f32 v120, v52, v53
	v_max3_f32 v5, v5, |v55|, |v39|
	v_cvt_pk_bf16_f32 v141, v38, v39
	v_cvt_pk_bf16_f32 v125, v36, v37
	v_cvt_pk_bf16_f32 v138, v24, v25
	v_cvt_pk_bf16_f32 v121, v26, v27
	v_max3_f32 v155, v4, |v24|, |v0|
	v_cvt_pk_bf16_f32 v142, v0, v1
	v_add_co_u32_e32 v0, vcc, s28, v82
	v_max3_f32 v6, v6, |v52|, |v36|
	v_max3_f32 v7, v7, |v53|, |v37|
	v_max3_f32 v154, v5, |v25|, |v1|
	v_addc_co_u32_e32 v1, vcc, 0, v83, vcc
	s_mov_b32 s28, 0x208000
	v_max3_f32 v153, v6, |v26|, |v2|
	v_max3_f32 v79, v7, |v27|, |v3|
	v_cvt_pk_bf16_f32 v123, v2, v3
	global_load_dwordx4 v[4:7], v[0:1], off nt
	v_add_co_u32_e32 v0, vcc, s28, v82
	s_mov_b32 s28, 0x408000
	s_nop 0
	v_addc_co_u32_e32 v1, vcc, 0, v83, vcc
	v_add_co_u32_e32 v8, vcc, s28, v82
	s_mov_b32 s28, 0x608000
	s_nop 0
	v_addc_co_u32_e32 v9, vcc, 0, v83, vcc
	v_add_co_u32_e32 v12, vcc, s28, v82
	s_mov_b32 s28, 0x808000
	s_nop 0
	v_addc_co_u32_e32 v13, vcc, 0, v83, vcc
	global_load_dwordx4 v[60:63], v[12:13], off nt
	v_add_co_u32_e32 v12, vcc, s28, v82
	s_mov_b32 s28, 0xa08000
	s_nop 0
	v_addc_co_u32_e32 v13, vcc, 0, v83, vcc
	global_load_dwordx4 v[16:19], v[12:13], off nt
	v_add_co_u32_e32 v12, vcc, s28, v82
	s_mov_b32 s28, 0xc08000
	s_nop 0
	v_addc_co_u32_e32 v13, vcc, 0, v83, vcc
	v_add_co_u32_e32 v20, vcc, s28, v82
	s_mov_b32 s28, 0xe08000
	s_nop 0
	v_addc_co_u32_e32 v21, vcc, 0, v83, vcc
	global_load_dwordx4 v[12:15], v[12:13], off nt
	ds_read2st64_b32 v[166:167], v88 offset0:12 offset1:14
	global_load_dwordx4 v[48:51], v[20:21], off nt
	v_add_co_u32_e32 v20, vcc, s28, v82
	s_mov_b32 s28, 0x1008000
	s_nop 0
	v_addc_co_u32_e32 v21, vcc, 0, v83, vcc
	global_load_dwordx4 v[56:59], v[20:21], off nt
	v_add_co_u32_e32 v20, vcc, s28, v82
	s_mov_b32 s28, 0x1208000
	s_nop 0
	v_addc_co_u32_e32 v21, vcc, 0, v83, vcc
	global_load_dwordx4 v[24:27], v[20:21], off nt
	v_add_co_u32_e32 v20, vcc, s28, v82
	s_mov_b32 s28, 0x1408000
	s_nop 0
	v_addc_co_u32_e32 v21, vcc, 0, v83, vcc
	v_add_co_u32_e32 v28, vcc, s28, v82
	s_mov_b32 s28, 0x1608000
	s_nop 0
	v_addc_co_u32_e32 v29, vcc, 0, v83, vcc
	global_load_dwordx4 v[20:23], v[20:21], off nt
	ds_read2st64_b32 v[170:171], v88 offset0:20 offset1:22
	global_load_dwordx4 v[44:47], v[28:29], off nt
	v_add_co_u32_e32 v28, vcc, s28, v82
	s_mov_b32 s28, 0x1808000
	s_nop 0
	v_addc_co_u32_e32 v29, vcc, 0, v83, vcc
	global_load_dwordx4 v[52:55], v[28:29], off nt
	v_add_co_u32_e32 v28, vcc, s28, v82
	s_mov_b32 s28, 0x1a08000
	s_nop 0
	v_addc_co_u32_e32 v29, vcc, 0, v83, vcc
	global_load_dwordx4 v[32:35], v[28:29], off nt
	v_add_co_u32_e32 v28, vcc, s28, v82
	s_mov_b32 s28, 0x1c08000
	s_nop 0
	v_addc_co_u32_e32 v29, vcc, 0, v83, vcc
	v_add_co_u32_e32 v36, vcc, s28, v82
	s_mov_b32 s28, 0x1e08000
	s_nop 0
	v_addc_co_u32_e32 v37, vcc, 0, v83, vcc
	v_add_co_u32_e32 v40, vcc, s28, v82
	global_load_dwordx4 v[28:31], v[28:29], off nt
	s_nop 0
	v_addc_co_u32_e32 v41, vcc, 0, v83, vcc
	global_load_dwordx4 v[36:39], v[36:37], off nt
	ds_read2st64_b32 v[160:161], v88 offset0:4 offset1:6
	global_load_dwordx4 v[0:3], v[0:1], off nt
	s_waitcnt lgkmcnt(2)
	v_mul_f32_e32 v166, 0x3e000000, v166
	global_load_dwordx4 v[8:11], v[8:9], off nt
	s_waitcnt lgkmcnt(1)
	v_mul_f32_e32 v170, 0x3e000000, v170
	global_load_dwordx4 v[40:43], v[40:41], off nt
	ds_read2st64_b32 v[174:175], v88 offset0:28 offset1:30
	s_waitcnt lgkmcnt(1)
	v_mul_f32_e32 v162, 0x3e000000, v161
	ds_read2_b32 v[156:157], v65 offset0:2 offset1:130
	s_waitcnt vmcnt(14)
	v_pk_mul_f32 v[62:63], v[62:63], v[162:163] op_sel_hi:[1,0]
	v_pk_mul_f32 v[60:61], v[60:61], v[162:163] op_sel_hi:[1,0]
	ds_read2st64_b32 v[162:163], v88 offset0:8 offset1:10
	s_waitcnt lgkmcnt(2)
	v_mul_f32_e32 v174, 0x3e000000, v174
	v_mul_f32_e32 v160, 0x3e000000, v160
	s_waitcnt lgkmcnt(1)
	v_mul_f32_e32 v158, 0x3e000000, v157
	v_mul_f32_e32 v156, 0x3e000000, v156
	s_waitcnt lgkmcnt(0)
	v_mul_f32_e32 v162, 0x3e000000, v162
	v_mul_f32_e32 v164, 0x3e000000, v163
	s_mov_b32 s28, 0xc000
	s_waitcnt vmcnt(11)
	v_pk_mul_f32 v[50:51], v[50:51], v[166:167] op_sel_hi:[1,0]
	v_pk_mul_f32 v[48:49], v[48:49], v[166:167] op_sel_hi:[1,0]
	v_mul_f32_e32 v166, 0x3e000000, v167
	s_waitcnt vmcnt(10)
	v_pk_mul_f32 v[58:59], v[58:59], v[166:167] op_sel_hi:[1,0]
	v_pk_mul_f32 v[56:57], v[56:57], v[166:167] op_sel_hi:[1,0]
	ds_read2st64_b32 v[166:167], v88 offset0:16 offset1:18
	s_waitcnt lgkmcnt(0)
	v_mul_f32_e32 v166, 0x3e000000, v166
	v_mul_f32_e32 v168, 0x3e000000, v167
	s_waitcnt vmcnt(7)
	v_pk_mul_f32 v[46:47], v[46:47], v[170:171] op_sel_hi:[1,0]
	v_pk_mul_f32 v[44:45], v[44:45], v[170:171] op_sel_hi:[1,0]
	v_mul_f32_e32 v170, 0x3e000000, v171
	s_waitcnt vmcnt(6)
	v_pk_mul_f32 v[54:55], v[54:55], v[170:171] op_sel_hi:[1,0]
	v_pk_mul_f32 v[52:53], v[52:53], v[170:171] op_sel_hi:[1,0]
	ds_read2st64_b32 v[170:171], v88 offset0:24 offset1:26
	s_waitcnt lgkmcnt(0)
	v_mul_f32_e32 v170, 0x3e000000, v170
	v_mul_f32_e32 v172, 0x3e000000, v171
	s_waitcnt vmcnt(3)
	v_pk_mul_f32 v[38:39], v[38:39], v[174:175] op_sel_hi:[1,0]
	v_pk_mul_f32 v[36:37], v[36:37], v[174:175] op_sel_hi:[1,0]
	v_mul_f32_e32 v174, 0x3e000000, v175
	s_waitcnt vmcnt(1)
	v_pk_mul_f32 v[10:11], v[10:11], v[160:161] op_sel_hi:[1,0]
	v_pk_mul_f32 v[8:9], v[8:9], v[160:161] op_sel_hi:[1,0]
	s_waitcnt vmcnt(0)
	v_pk_mul_f32 v[40:41], v[40:41], v[174:175] op_sel_hi:[1,0]
	v_pk_mul_f32 v[42:43], v[42:43], v[174:175] op_sel_hi:[1,0]
	v_pk_fma_f32 v[160:161], v[6:7], v[156:157], v[10:11] op_sel_hi:[1,0,1]
	v_pk_fma_f32 v[174:175], v[4:5], v[156:157], v[8:9] op_sel_hi:[1,0,1]
	v_pk_fma_f32 v[6:7], v[6:7], v[156:157], v[10:11] op_sel_hi:[1,0,1] neg_lo:[0,0,1] neg_hi:[0,0,1]
	v_pk_fma_f32 v[4:5], v[4:5], v[156:157], v[8:9] op_sel_hi:[1,0,1] neg_lo:[0,0,1] neg_hi:[0,0,1]
	v_pk_fma_f32 v[8:9], v[2:3], v[158:159], v[62:63] op_sel_hi:[1,0,1]
	v_pk_fma_f32 v[10:11], v[0:1], v[158:159], v[60:61] op_sel_hi:[1,0,1]
	v_pk_fma_f32 v[2:3], v[2:3], v[158:159], v[62:63] op_sel_hi:[1,0,1] neg_lo:[0,0,1] neg_hi:[0,0,1]
	v_pk_fma_f32 v[0:1], v[0:1], v[158:159], v[60:61] op_sel_hi:[1,0,1] neg_lo:[0,0,1] neg_hi:[0,0,1]
	v_pk_fma_f32 v[60:61], v[18:19], v[162:163], v[50:51] op_sel_hi:[1,0,1]
	v_pk_fma_f32 v[62:63], v[16:17], v[162:163], v[48:49] op_sel_hi:[1,0,1]
	v_pk_fma_f32 v[18:19], v[18:19], v[162:163], v[50:51] op_sel_hi:[1,0,1] neg_lo:[0,0,1] neg_hi:[0,0,1]
	v_pk_fma_f32 v[16:17], v[16:17], v[162:163], v[48:49] op_sel_hi:[1,0,1] neg_lo:[0,0,1] neg_hi:[0,0,1]
	v_pk_fma_f32 v[48:49], v[14:15], v[164:165], v[58:59] op_sel_hi:[1,0,1]
	v_pk_fma_f32 v[50:51], v[12:13], v[164:165], v[56:57] op_sel_hi:[1,0,1]
	v_pk_fma_f32 v[14:15], v[14:15], v[164:165], v[58:59] op_sel_hi:[1,0,1] neg_lo:[0,0,1] neg_hi:[0,0,1]
	v_pk_fma_f32 v[12:13], v[12:13], v[164:165], v[56:57] op_sel_hi:[1,0,1] neg_lo:[0,0,1] neg_hi:[0,0,1]
	v_pk_fma_f32 v[56:57], v[26:27], v[166:167], v[46:47] op_sel_hi:[1,0,1]
	v_pk_fma_f32 v[58:59], v[24:25], v[166:167], v[44:45] op_sel_hi:[1,0,1]
	v_pk_fma_f32 v[26:27], v[26:27], v[166:167], v[46:47] op_sel_hi:[1,0,1] neg_lo:[0,0,1] neg_hi:[0,0,1]
	v_pk_fma_f32 v[24:25], v[24:25], v[166:167], v[44:45] op_sel_hi:[1,0,1] neg_lo:[0,0,1] neg_hi:[0,0,1]
	v_pk_fma_f32 v[44:45], v[22:23], v[168:169], v[54:55] op_sel_hi:[1,0,1]
	v_pk_fma_f32 v[46:47], v[20:21], v[168:169], v[52:53] op_sel_hi:[1,0,1]
	v_pk_fma_f32 v[22:23], v[22:23], v[168:169], v[54:55] op_sel_hi:[1,0,1] neg_lo:[0,0,1] neg_hi:[0,0,1]
	v_pk_fma_f32 v[20:21], v[20:21], v[168:169], v[52:53] op_sel_hi:[1,0,1] neg_lo:[0,0,1] neg_hi:[0,0,1]
	v_pk_fma_f32 v[52:53], v[34:35], v[170:171], v[38:39] op_sel_hi:[1,0,1]
	v_pk_fma_f32 v[54:55], v[32:33], v[170:171], v[36:37] op_sel_hi:[1,0,1]
	v_pk_fma_f32 v[34:35], v[34:35], v[170:171], v[38:39] op_sel_hi:[1,0,1] neg_lo:[0,0,1] neg_hi:[0,0,1]
	v_pk_fma_f32 v[38:39], v[28:29], v[172:173], v[40:41] op_sel_hi:[1,0,1]
	v_pk_fma_f32 v[32:33], v[32:33], v[170:171], v[36:37] op_sel_hi:[1,0,1] neg_lo:[0,0,1] neg_hi:[0,0,1]
	v_pk_fma_f32 v[36:37], v[30:31], v[172:173], v[42:43] op_sel_hi:[1,0,1]
	v_pk_fma_f32 v[30:31], v[30:31], v[172:173], v[42:43] op_sel_hi:[1,0,1] neg_lo:[0,0,1] neg_hi:[0,0,1]
	v_pk_fma_f32 v[28:29], v[28:29], v[172:173], v[40:41] op_sel_hi:[1,0,1] neg_lo:[0,0,1] neg_hi:[0,0,1]
	v_pk_add_f32 v[42:43], v[174:175], v[62:63]
	v_pk_add_f32 v[158:159], v[10:11], v[50:51]
	v_sub_f32_e32 v11, v11, v51
	v_sub_f32_e32 v10, v10, v50
	v_pk_add_f32 v[50:51], v[4:5], v[16:17]
	v_sub_f32_e32 v5, v5, v17
	v_sub_f32_e32 v4, v4, v16
	v_pk_add_f32 v[16:17], v[2:3], v[14:15]
	v_sub_f32_e32 v3, v3, v15
	v_sub_f32_e32 v2, v2, v14
	v_pk_add_f32 v[14:15], v[58:59], v[54:55]
	v_sub_f32_e32 v55, v59, v55
	v_sub_f32_e32 v54, v58, v54
	v_pk_add_f32 v[58:59], v[46:47], v[38:39]
	v_pk_add_f32 v[40:41], v[160:161], v[60:61]
	v_pk_add_f32 v[156:157], v[8:9], v[48:49]
	v_sub_f32_e32 v9, v9, v49
	v_sub_f32_e32 v8, v8, v48
	v_pk_add_f32 v[48:49], v[6:7], v[18:19]
	v_sub_f32_e32 v7, v7, v19
	v_sub_f32_e32 v6, v6, v18
	v_pk_add_f32 v[18:19], v[0:1], v[12:13]
	v_sub_f32_e32 v1, v1, v13
	v_sub_f32_e32 v0, v0, v12
	v_pk_add_f32 v[12:13], v[56:57], v[52:53]
	v_sub_f32_e32 v53, v57, v53
	v_sub_f32_e32 v52, v56, v52
	v_pk_add_f32 v[56:57], v[44:45], v[36:37]
	v_sub_f32_e32 v37, v45, v37
	v_sub_f32_e32 v36, v44, v36
	v_sub_f32_e32 v39, v47, v39
	v_sub_f32_e32 v38, v46, v38
	v_pk_add_f32 v[44:45], v[26:27], v[34:35]
	v_pk_add_f32 v[46:47], v[24:25], v[32:33]
	v_sub_f32_e32 v27, v27, v35
	v_sub_f32_e32 v26, v26, v34
	v_sub_f32_e32 v25, v25, v33
	v_sub_f32_e32 v24, v24, v32
	v_pk_add_f32 v[32:33], v[22:23], v[30:31]
	v_pk_add_f32 v[34:35], v[20:21], v[28:29]
	v_sub_f32_e32 v23, v23, v31
	v_sub_f32_e32 v22, v22, v30
	v_sub_f32_e32 v21, v21, v29
	v_sub_f32_e32 v20, v20, v28
	v_pk_add_f32 v[30:31], v[42:43], v[14:15]
	v_sub_f32_e32 v171, v42, v14
	v_sub_f32_e32 v172, v43, v15
	v_pk_add_f32 v[14:15], v[158:159], v[58:59]
	v_sub_f32_e32 v63, v175, v63
	v_sub_f32_e32 v62, v174, v62
	v_pk_add_f32 v[28:29], v[40:41], v[12:13]
	v_sub_f32_e32 v169, v40, v12
	v_sub_f32_e32 v170, v41, v13
	v_pk_add_f32 v[12:13], v[156:157], v[56:57]
	v_sub_f32_e32 v57, v157, v57
	v_sub_f32_e32 v56, v156, v56
	v_pk_add_f32 v[40:41], v[48:49], v[44:45]
	v_pk_add_f32 v[42:43], v[50:51], v[46:47]
	v_sub_f32_e32 v48, v48, v44
	v_sub_f32_e32 v49, v49, v45
	v_sub_f32_e32 v50, v50, v46
	v_sub_f32_e32 v51, v51, v47
	v_pk_add_f32 v[44:45], v[16:17], v[32:33]
	v_pk_add_f32 v[46:47], v[18:19], v[34:35]
	v_sub_f32_e32 v156, v17, v33
	v_sub_f32_e32 v157, v16, v32
	v_pk_add_f32 v[32:33], v[8:9], v[36:37]
	v_sub_f32_e32 v37, v9, v37
	v_sub_f32_e32 v36, v8, v36
	v_pk_add_f32 v[8:9], v[6:7], v[26:27]
	v_sub_f32_e32 v26, v6, v26
	v_sub_f32_e32 v27, v7, v27
	v_pk_add_f32 v[6:7], v[0:1], v[20:21]
	v_sub_f32_e32 v0, v0, v20
	v_max3_f32 v20, v155, |v30|, |v14|
	v_sub_f32_e32 v61, v161, v61
	v_sub_f32_e32 v60, v160, v60
	v_sub_f32_e32 v58, v158, v58
	v_sub_f32_e32 v158, v19, v35
	v_sub_f32_e32 v173, v18, v34
	v_pk_add_f32 v[18:19], v[62:63], v[54:55]
	v_pk_add_f32 v[34:35], v[10:11], v[38:39]
	v_sub_f32_e32 v39, v11, v39
	v_sub_f32_e32 v38, v10, v38
	v_pk_add_f32 v[10:11], v[4:5], v[24:25]
	v_sub_f32_e32 v24, v4, v24
	v_sub_f32_e32 v25, v5, v25
	v_pk_add_f32 v[4:5], v[2:3], v[22:23]
	v_sub_f32_e32 v2, v2, v22
	v_sub_f32_e32 v1, v1, v21
	v_cvt_pk_bf16_f32 v184, v30, v31
	v_cvt_pk_bf16_f32 v168, v28, v29
	v_max3_f32 v21, v154, |v31|, |v15|
	v_max3_f32 v22, v153, |v28|, |v12|
	v_cvt_pk_bf16_f32 v183, v14, v15
	v_cvt_pk_bf16_f32 v167, v12, v13
	v_max3_f32 v12, v20, |v42|, |v46|
	v_pk_add_f32 v[16:17], v[60:61], v[52:53]
	v_sub_f32_e32 v3, v3, v23
	v_max3_f32 v23, v79, |v29|, |v13|
	v_max3_f32 v13, v21, |v43|, |v47|
	v_max3_f32 v14, v22, |v40|, |v44|
	v_max3_f32 v12, v12, |v18|, |v34|
	v_cvt_pk_bf16_f32 v182, v42, v43
	v_cvt_pk_bf16_f32 v166, v40, v41
	v_max3_f32 v15, v23, |v41|, |v45|
	v_cvt_pk_bf16_f32 v181, v46, v47
	v_cvt_pk_bf16_f32 v165, v44, v45
	v_cvt_pk_bf16_f32 v180, v18, v19
	v_cvt_pk_bf16_f32 v164, v16, v17
	v_max3_f32 v13, v13, |v19|, |v35|
	v_max3_f32 v14, v14, |v16|, |v32|
	v_cvt_pk_bf16_f32 v179, v34, v35
	v_cvt_pk_bf16_f32 v163, v32, v33
	v_cvt_pk_bf16_f32 v178, v10, v11
	v_max3_f32 v10, v12, |v10|, |v6|
	v_sub_f32_e32 v59, v159, v59
	v_max3_f32 v15, v15, |v17|, |v33|
	v_cvt_pk_bf16_f32 v162, v8, v9
	v_max3_f32 v11, v13, |v11|, |v7|
	v_max3_f32 v8, v14, |v8|, |v4|
	v_cvt_pk_bf16_f32 v177, v6, v7
	v_cvt_pk_bf16_f32 v161, v4, v5
	v_max3_f32 v4, v10, |v171|, |v58|
	v_sub_f32_e32 v54, v62, v54
	v_max3_f32 v9, v15, |v9|, |v5|
	v_max3_f32 v5, v11, |v172|, |v59|
	v_max3_f32 v4, v4, |v50|, |v173|
	v_sub_f32_e32 v55, v63, v55
	v_max3_f32 v6, v8, |v169|, |v56|
	v_max3_f32 v7, v9, |v170|, |v57|
	v_max3_f32 v5, v5, |v51|, |v158|
	v_max3_f32 v4, v4, |v54|, |v38|
	v_sub_f32_e32 v52, v60, v52
	v_sub_f32_e32 v53, v61, v53
	v_cvt_pk_bf16_f32 v176, v171, v172
	v_cvt_pk_bf16_f32 v160, v169, v170
	v_cvt_pk_bf16_f32 v175, v58, v59
	v_cvt_pk_bf16_f32 v159, v56, v57
	v_cvt_pk_bf16_f32 v171, v50, v51
	v_cvt_pk_bf16_f32 v155, v48, v49
	v_max3_f32 v6, v6, |v48|, |v157|
	v_max3_f32 v7, v7, |v49|, |v156|
	v_cvt_pk_bf16_f32 v172, v173, v158
	v_cvt_pk_bf16_f32 v156, v157, v156
	v_cvt_pk_bf16_f32 v169, v54, v55
	v_cvt_pk_bf16_f32 v153, v52, v53
	v_max3_f32 v5, v5, |v55|, |v39|
	v_cvt_pk_bf16_f32 v173, v38, v39
	v_cvt_pk_bf16_f32 v157, v36, v37
	v_cvt_pk_bf16_f32 v170, v24, v25
	v_cvt_pk_bf16_f32 v154, v26, v27
	v_max3_f32 v187, v4, |v24|, |v0|
	v_cvt_pk_bf16_f32 v174, v0, v1
	v_add_co_u32_e32 v0, vcc, s28, v82
	v_max3_f32 v6, v6, |v52|, |v36|
	v_max3_f32 v7, v7, |v53|, |v37|
	v_max3_f32 v186, v5, |v25|, |v1|
	v_addc_co_u32_e32 v1, vcc, 0, v83, vcc
	s_mov_b32 s28, 0x20c000
	v_max3_f32 v185, v6, |v26|, |v2|
	v_max3_f32 v79, v7, |v27|, |v3|
	v_cvt_pk_bf16_f32 v158, v2, v3
	global_load_dwordx4 v[4:7], v[0:1], off nt
	v_add_co_u32_e32 v0, vcc, s28, v82
	s_mov_b32 s28, 0x40c000
	s_nop 0
	v_addc_co_u32_e32 v1, vcc, 0, v83, vcc
	v_add_co_u32_e32 v8, vcc, s28, v82
	s_mov_b32 s28, 0x60c000
	s_nop 0
	v_addc_co_u32_e32 v9, vcc, 0, v83, vcc
	v_add_co_u32_e32 v12, vcc, s28, v82
	s_mov_b32 s28, 0x80c000
	s_nop 0
	v_addc_co_u32_e32 v13, vcc, 0, v83, vcc
	global_load_dwordx4 v[60:63], v[12:13], off nt
	v_add_co_u32_e32 v12, vcc, s28, v82
	s_mov_b32 s28, 0xa0c000
	s_nop 0
	v_addc_co_u32_e32 v13, vcc, 0, v83, vcc
	global_load_dwordx4 v[16:19], v[12:13], off nt
	v_add_co_u32_e32 v12, vcc, s28, v82
	s_mov_b32 s28, 0xc0c000
	s_nop 0
	v_addc_co_u32_e32 v13, vcc, 0, v83, vcc
	v_add_co_u32_e32 v20, vcc, s28, v82
	s_mov_b32 s28, 0xe0c000
	s_nop 0
	v_addc_co_u32_e32 v21, vcc, 0, v83, vcc
	global_load_dwordx4 v[12:15], v[12:13], off nt
	ds_read2st64_b32 v[196:197], v89 offset0:12 offset1:14
	global_load_dwordx4 v[48:51], v[20:21], off nt
	v_add_co_u32_e32 v20, vcc, s28, v82
	s_mov_b32 s28, 0x100c000
	s_nop 0
	v_addc_co_u32_e32 v21, vcc, 0, v83, vcc
	global_load_dwordx4 v[56:59], v[20:21], off nt
	v_add_co_u32_e32 v20, vcc, s28, v82
	s_mov_b32 s28, 0x120c000
	s_nop 0
	v_addc_co_u32_e32 v21, vcc, 0, v83, vcc
	global_load_dwordx4 v[24:27], v[20:21], off nt
	v_add_co_u32_e32 v20, vcc, s28, v82
	s_mov_b32 s28, 0x140c000
	s_nop 0
	v_addc_co_u32_e32 v21, vcc, 0, v83, vcc
	v_add_co_u32_e32 v28, vcc, s28, v82
	s_mov_b32 s28, 0x160c000
	s_nop 0
	v_addc_co_u32_e32 v29, vcc, 0, v83, vcc
	global_load_dwordx4 v[20:23], v[20:21], off nt
	ds_read2st64_b32 v[200:201], v89 offset0:20 offset1:22
	global_load_dwordx4 v[44:47], v[28:29], off nt
	v_add_co_u32_e32 v28, vcc, s28, v82
	s_mov_b32 s28, 0x180c000
	s_nop 0
	v_addc_co_u32_e32 v29, vcc, 0, v83, vcc
	global_load_dwordx4 v[52:55], v[28:29], off nt
	v_add_co_u32_e32 v28, vcc, s28, v82
	s_mov_b32 s28, 0x1a0c000
	s_nop 0
	v_addc_co_u32_e32 v29, vcc, 0, v83, vcc
	global_load_dwordx4 v[32:35], v[28:29], off nt
	v_add_co_u32_e32 v28, vcc, s28, v82
	s_mov_b32 s28, 0x1c0c000
	s_nop 0
	v_addc_co_u32_e32 v29, vcc, 0, v83, vcc
	v_add_co_u32_e32 v36, vcc, s28, v82
	s_mov_b32 s28, 0x1e0c000
	s_nop 0
	v_addc_co_u32_e32 v37, vcc, 0, v83, vcc
	v_add_co_u32_e32 v40, vcc, s28, v82
	global_load_dwordx4 v[28:31], v[28:29], off nt
	s_nop 0
	v_addc_co_u32_e32 v41, vcc, 0, v83, vcc
	global_load_dwordx4 v[36:39], v[36:37], off nt
	ds_read2st64_b32 v[190:191], v89 offset0:4 offset1:6
	global_load_dwordx4 v[0:3], v[0:1], off nt
	s_waitcnt lgkmcnt(2)
	v_mul_f32_e32 v196, 0x3e000000, v196
	global_load_dwordx4 v[8:11], v[8:9], off nt
	s_waitcnt lgkmcnt(1)
	v_mul_f32_e32 v200, 0x3e000000, v200
	global_load_dwordx4 v[40:43], v[40:41], off nt
	ds_read2st64_b32 v[204:205], v89 offset0:28 offset1:30
	s_waitcnt lgkmcnt(1)
	v_mul_f32_e32 v192, 0x3e000000, v191
	ds_read2_b32 v[82:83], v65 offset0:3 offset1:131
	s_waitcnt vmcnt(14)
	v_pk_mul_f32 v[62:63], v[62:63], v[192:193] op_sel_hi:[1,0]
	v_pk_mul_f32 v[60:61], v[60:61], v[192:193] op_sel_hi:[1,0]
	ds_read2st64_b32 v[192:193], v89 offset0:8 offset1:10
	s_waitcnt lgkmcnt(2)
	v_mul_f32_e32 v204, 0x3e000000, v204
	v_mul_f32_e32 v190, 0x3e000000, v190
	s_waitcnt lgkmcnt(1)
	v_mul_f32_e32 v188, 0x3e000000, v83
	v_mul_f32_e32 v82, 0x3e000000, v82
	s_waitcnt lgkmcnt(0)
	v_mul_f32_e32 v192, 0x3e000000, v192
	v_mul_f32_e32 v194, 0x3e000000, v193
	s_waitcnt vmcnt(11)
	v_pk_mul_f32 v[50:51], v[50:51], v[196:197] op_sel_hi:[1,0]
	v_pk_mul_f32 v[48:49], v[48:49], v[196:197] op_sel_hi:[1,0]
	v_mul_f32_e32 v196, 0x3e000000, v197
	s_waitcnt vmcnt(10)
	v_pk_mul_f32 v[58:59], v[58:59], v[196:197] op_sel_hi:[1,0]
	v_pk_mul_f32 v[56:57], v[56:57], v[196:197] op_sel_hi:[1,0]
	ds_read2st64_b32 v[196:197], v89 offset0:16 offset1:18
	s_waitcnt lgkmcnt(0)
	v_mul_f32_e32 v196, 0x3e000000, v196
	v_mul_f32_e32 v198, 0x3e000000, v197
	s_waitcnt vmcnt(7)
	v_pk_mul_f32 v[46:47], v[46:47], v[200:201] op_sel_hi:[1,0]
	v_pk_mul_f32 v[44:45], v[44:45], v[200:201] op_sel_hi:[1,0]
	v_mul_f32_e32 v200, 0x3e000000, v201
	s_waitcnt vmcnt(6)
	v_pk_mul_f32 v[54:55], v[54:55], v[200:201] op_sel_hi:[1,0]
	v_pk_mul_f32 v[52:53], v[52:53], v[200:201] op_sel_hi:[1,0]
	ds_read2st64_b32 v[200:201], v89 offset0:24 offset1:26
	s_waitcnt lgkmcnt(0)
	v_mul_f32_e32 v200, 0x3e000000, v200
	v_mul_f32_e32 v202, 0x3e000000, v201
	s_waitcnt vmcnt(3)
	v_pk_mul_f32 v[38:39], v[38:39], v[204:205] op_sel_hi:[1,0]
	v_pk_mul_f32 v[36:37], v[36:37], v[204:205] op_sel_hi:[1,0]
	v_mul_f32_e32 v204, 0x3e000000, v205
	s_waitcnt vmcnt(1)
	v_pk_mul_f32 v[10:11], v[10:11], v[190:191] op_sel_hi:[1,0]
	v_pk_mul_f32 v[8:9], v[8:9], v[190:191] op_sel_hi:[1,0]
	s_waitcnt vmcnt(0)
	v_pk_mul_f32 v[40:41], v[40:41], v[204:205] op_sel_hi:[1,0]
	v_pk_mul_f32 v[42:43], v[42:43], v[204:205] op_sel_hi:[1,0]
	v_pk_fma_f32 v[190:191], v[6:7], v[82:83], v[10:11] op_sel_hi:[1,0,1]
	v_pk_fma_f32 v[204:205], v[4:5], v[82:83], v[8:9] op_sel_hi:[1,0,1]
	v_pk_fma_f32 v[6:7], v[6:7], v[82:83], v[10:11] op_sel_hi:[1,0,1] neg_lo:[0,0,1] neg_hi:[0,0,1]
	v_pk_fma_f32 v[4:5], v[4:5], v[82:83], v[8:9] op_sel_hi:[1,0,1] neg_lo:[0,0,1] neg_hi:[0,0,1]
	v_pk_fma_f32 v[8:9], v[2:3], v[188:189], v[62:63] op_sel_hi:[1,0,1]
	v_pk_fma_f32 v[10:11], v[0:1], v[188:189], v[60:61] op_sel_hi:[1,0,1]
	v_pk_fma_f32 v[2:3], v[2:3], v[188:189], v[62:63] op_sel_hi:[1,0,1] neg_lo:[0,0,1] neg_hi:[0,0,1]
	v_pk_fma_f32 v[0:1], v[0:1], v[188:189], v[60:61] op_sel_hi:[1,0,1] neg_lo:[0,0,1] neg_hi:[0,0,1]
	v_pk_fma_f32 v[60:61], v[18:19], v[192:193], v[50:51] op_sel_hi:[1,0,1]
	v_pk_fma_f32 v[62:63], v[16:17], v[192:193], v[48:49] op_sel_hi:[1,0,1]
	v_pk_fma_f32 v[18:19], v[18:19], v[192:193], v[50:51] op_sel_hi:[1,0,1] neg_lo:[0,0,1] neg_hi:[0,0,1]
	v_pk_fma_f32 v[16:17], v[16:17], v[192:193], v[48:49] op_sel_hi:[1,0,1] neg_lo:[0,0,1] neg_hi:[0,0,1]
	v_pk_fma_f32 v[48:49], v[14:15], v[194:195], v[58:59] op_sel_hi:[1,0,1]
	v_pk_fma_f32 v[50:51], v[12:13], v[194:195], v[56:57] op_sel_hi:[1,0,1]
	v_pk_fma_f32 v[14:15], v[14:15], v[194:195], v[58:59] op_sel_hi:[1,0,1] neg_lo:[0,0,1] neg_hi:[0,0,1]
	v_pk_fma_f32 v[12:13], v[12:13], v[194:195], v[56:57] op_sel_hi:[1,0,1] neg_lo:[0,0,1] neg_hi:[0,0,1]
	v_pk_fma_f32 v[56:57], v[26:27], v[196:197], v[46:47] op_sel_hi:[1,0,1]
	v_pk_fma_f32 v[58:59], v[24:25], v[196:197], v[44:45] op_sel_hi:[1,0,1]
	v_pk_fma_f32 v[26:27], v[26:27], v[196:197], v[46:47] op_sel_hi:[1,0,1] neg_lo:[0,0,1] neg_hi:[0,0,1]
	v_pk_fma_f32 v[24:25], v[24:25], v[196:197], v[44:45] op_sel_hi:[1,0,1] neg_lo:[0,0,1] neg_hi:[0,0,1]
	v_pk_fma_f32 v[44:45], v[22:23], v[198:199], v[54:55] op_sel_hi:[1,0,1]
	v_pk_fma_f32 v[46:47], v[20:21], v[198:199], v[52:53] op_sel_hi:[1,0,1]
	v_pk_fma_f32 v[22:23], v[22:23], v[198:199], v[54:55] op_sel_hi:[1,0,1] neg_lo:[0,0,1] neg_hi:[0,0,1]
	v_pk_fma_f32 v[20:21], v[20:21], v[198:199], v[52:53] op_sel_hi:[1,0,1] neg_lo:[0,0,1] neg_hi:[0,0,1]
	v_pk_fma_f32 v[52:53], v[34:35], v[200:201], v[38:39] op_sel_hi:[1,0,1]
	v_pk_fma_f32 v[54:55], v[32:33], v[200:201], v[36:37] op_sel_hi:[1,0,1]
	v_pk_fma_f32 v[34:35], v[34:35], v[200:201], v[38:39] op_sel_hi:[1,0,1] neg_lo:[0,0,1] neg_hi:[0,0,1]
	v_pk_fma_f32 v[38:39], v[28:29], v[202:203], v[40:41] op_sel_hi:[1,0,1]
	v_pk_fma_f32 v[32:33], v[32:33], v[200:201], v[36:37] op_sel_hi:[1,0,1] neg_lo:[0,0,1] neg_hi:[0,0,1]
	v_pk_fma_f32 v[36:37], v[30:31], v[202:203], v[42:43] op_sel_hi:[1,0,1]
	v_pk_fma_f32 v[30:31], v[30:31], v[202:203], v[42:43] op_sel_hi:[1,0,1] neg_lo:[0,0,1] neg_hi:[0,0,1]
	v_pk_fma_f32 v[28:29], v[28:29], v[202:203], v[40:41] op_sel_hi:[1,0,1] neg_lo:[0,0,1] neg_hi:[0,0,1]
	v_pk_add_f32 v[42:43], v[204:205], v[62:63]
	v_pk_add_f32 v[188:189], v[10:11], v[50:51]
	v_sub_f32_e32 v11, v11, v51
	v_sub_f32_e32 v10, v10, v50
	v_pk_add_f32 v[50:51], v[4:5], v[16:17]
	v_sub_f32_e32 v5, v5, v17
	v_sub_f32_e32 v4, v4, v16
	v_pk_add_f32 v[16:17], v[2:3], v[14:15]
	v_sub_f32_e32 v3, v3, v15
	v_sub_f32_e32 v2, v2, v14
	v_pk_add_f32 v[14:15], v[58:59], v[54:55]
	v_sub_f32_e32 v55, v59, v55
	v_sub_f32_e32 v54, v58, v54
	v_pk_add_f32 v[58:59], v[46:47], v[38:39]
	v_pk_add_f32 v[40:41], v[190:191], v[60:61]
	v_pk_add_f32 v[82:83], v[8:9], v[48:49]
	v_sub_f32_e32 v9, v9, v49
	v_sub_f32_e32 v8, v8, v48
	v_pk_add_f32 v[48:49], v[6:7], v[18:19]
	v_sub_f32_e32 v7, v7, v19
	v_sub_f32_e32 v6, v6, v18
	v_pk_add_f32 v[18:19], v[0:1], v[12:13]
	v_sub_f32_e32 v1, v1, v13
	v_sub_f32_e32 v0, v0, v12
	v_pk_add_f32 v[12:13], v[56:57], v[52:53]
	v_sub_f32_e32 v53, v57, v53
	v_sub_f32_e32 v52, v56, v52
	v_pk_add_f32 v[56:57], v[44:45], v[36:37]
	v_sub_f32_e32 v37, v45, v37
	v_sub_f32_e32 v36, v44, v36
	v_sub_f32_e32 v39, v47, v39
	v_sub_f32_e32 v38, v46, v38
	v_pk_add_f32 v[44:45], v[26:27], v[34:35]
	v_pk_add_f32 v[46:47], v[24:25], v[32:33]
	v_sub_f32_e32 v27, v27, v35
	v_sub_f32_e32 v26, v26, v34
	v_sub_f32_e32 v25, v25, v33
	v_sub_f32_e32 v24, v24, v32
	v_pk_add_f32 v[32:33], v[22:23], v[30:31]
	v_pk_add_f32 v[34:35], v[20:21], v[28:29]
	v_sub_f32_e32 v23, v23, v31
	v_sub_f32_e32 v22, v22, v30
	v_pk_add_f32 v[30:31], v[42:43], v[14:15]
	v_sub_f32_e32 v192, v42, v14
	v_sub_f32_e32 v193, v43, v15
	v_pk_add_f32 v[14:15], v[188:189], v[58:59]
	v_sub_f32_e32 v61, v191, v61
	v_sub_f32_e32 v60, v190, v60
	v_sub_f32_e32 v63, v205, v63
	v_sub_f32_e32 v62, v204, v62
	v_sub_f32_e32 v21, v21, v29
	v_sub_f32_e32 v20, v20, v28
	v_pk_add_f32 v[28:29], v[40:41], v[12:13]
	v_sub_f32_e32 v190, v40, v12
	v_sub_f32_e32 v191, v41, v13
	v_pk_add_f32 v[12:13], v[82:83], v[56:57]
	v_sub_f32_e32 v57, v83, v57
	v_sub_f32_e32 v56, v82, v56
	v_sub_f32_e32 v59, v189, v59
	v_sub_f32_e32 v58, v188, v58
	v_pk_add_f32 v[40:41], v[48:49], v[44:45]
	v_pk_add_f32 v[42:43], v[50:51], v[46:47]
	v_sub_f32_e32 v82, v48, v44
	v_sub_f32_e32 v83, v49, v45
	v_sub_f32_e32 v188, v50, v46
	v_sub_f32_e32 v189, v51, v47
	v_pk_add_f32 v[44:45], v[16:17], v[32:33]
	v_pk_add_f32 v[46:47], v[18:19], v[34:35]
	v_sub_f32_e32 v195, v16, v32
	v_max3_f32 v16, v187, |v30|, |v14|
	v_sub_f32_e32 v196, v19, v35
	v_sub_f32_e32 v197, v18, v34
	v_pk_add_f32 v[48:49], v[60:61], v[52:53]
	v_pk_add_f32 v[50:51], v[62:63], v[54:55]
	v_sub_f32_e32 v60, v60, v52
	v_sub_f32_e32 v61, v61, v53
	v_sub_f32_e32 v62, v62, v54
	v_sub_f32_e32 v63, v63, v55
	v_pk_add_f32 v[52:53], v[8:9], v[36:37]
	v_pk_add_f32 v[54:55], v[10:11], v[38:39]
	v_sub_f32_e32 v37, v9, v37
	v_sub_f32_e32 v198, v8, v36
	v_sub_f32_e32 v39, v11, v39
	v_sub_f32_e32 v38, v10, v38
	v_pk_add_f32 v[8:9], v[6:7], v[26:27]
	v_pk_add_f32 v[10:11], v[4:5], v[24:25]
	v_sub_f32_e32 v199, v6, v26
	v_sub_f32_e32 v200, v7, v27
	v_sub_f32_e32 v201, v4, v24
	v_sub_f32_e32 v202, v5, v25
	v_pk_add_f32 v[4:5], v[2:3], v[22:23]
	v_pk_add_f32 v[6:7], v[0:1], v[20:21]
	v_sub_f32_e32 v2, v2, v22
	v_sub_f32_e32 v1, v1, v21
	v_sub_f32_e32 v0, v0, v20
	v_cvt_pk_bf16_f32 v36, v30, v31
	v_cvt_pk_bf16_f32 v19, v28, v29
	v_max3_f32 v20, v186, |v31|, |v15|
	v_max3_f32 v21, v185, |v28|, |v12|
	v_max3_f32 v22, v79, |v29|, |v13|
	v_cvt_pk_bf16_f32 v35, v14, v15
	v_cvt_pk_bf16_f32 v18, v12, v13
	v_max3_f32 v12, v16, |v42|, |v46|
	v_max3_f32 v13, v20, |v43|, |v47|
	v_max3_f32 v14, v21, |v40|, |v44|
	v_max3_f32 v20, v22, |v41|, |v45|
	v_max3_f32 v12, v12, |v50|, |v54|
	v_sub_f32_e32 v194, v17, v33
	v_cvt_pk_bf16_f32 v34, v42, v43
	v_cvt_pk_bf16_f32 v17, v40, v41
	v_cvt_pk_bf16_f32 v33, v46, v47
	v_cvt_pk_bf16_f32 v16, v44, v45
	v_cvt_pk_bf16_f32 v32, v50, v51
	v_cvt_pk_bf16_f32 v15, v48, v49
	v_max3_f32 v22, v14, |v48|, |v52|
	v_max3_f32 v20, v20, |v49|, |v53|
	v_cvt_pk_bf16_f32 v31, v54, v55
	v_cvt_pk_bf16_f32 v14, v52, v53
	v_cvt_pk_bf16_f32 v30, v10, v11
	v_max3_f32 v10, v12, |v10|, |v6|
	v_max3_f32 v21, v13, |v51|, |v55|
	v_cvt_pk_bf16_f32 v13, v8, v9
	v_max3_f32 v8, v22, |v8|, |v4|
	v_max3_f32 v9, v20, |v9|, |v5|
	v_cvt_pk_bf16_f32 v29, v6, v7
	v_cvt_pk_bf16_f32 v12, v4, v5
	v_max3_f32 v4, v10, |v192|, |v58|
	v_max3_f32 v21, v21, |v11|, |v7|
	v_max3_f32 v7, v9, |v191|, |v57|
	v_max3_f32 v4, v4, |v188|, |v197|
	v_sub_f32_e32 v3, v3, v23
	v_max3_f32 v5, v21, |v193|, |v59|
	v_max3_f32 v6, v8, |v190|, |v56|
	v_max3_f32 v20, v7, |v83|, |v194|
	v_max3_f32 v23, v4, |v62|, |v38|
	v_max3_f32 v5, v5, |v189|, |v196|
	v_max3_f32 v6, v6, |v82|, |v195|
	v_max3_f32 v20, v20, |v61|, |v37|
	v_max3_f32 v23, v23, |v201|, |v0|
	v_cvt_pk_bf16_f32 v28, v192, v193
	v_cvt_pk_bf16_f32 v11, v190, v191
	v_cvt_pk_bf16_f32 v27, v58, v59
	v_cvt_pk_bf16_f32 v10, v56, v57
	v_cvt_pk_bf16_f32 v26, v188, v189
	v_cvt_pk_bf16_f32 v9, v82, v83
	v_cvt_pk_bf16_f32 v25, v197, v196
	v_cvt_pk_bf16_f32 v8, v195, v194
	v_cvt_pk_bf16_f32 v24, v62, v63
	v_cvt_pk_bf16_f32 v7, v60, v61
	v_max3_f32 v5, v5, |v63|, |v39|
	v_max3_f32 v40, v6, |v60|, |v198|
	v_cvt_pk_bf16_f32 v22, v38, v39
	v_cvt_pk_bf16_f32 v6, v198, v37
	v_cvt_pk_bf16_f32 v21, v201, v202
	v_cvt_pk_bf16_f32 v4, v199, v200
	v_max3_f32 v39, v20, |v200|, |v3|
	v_cvt_pk_bf16_f32 v20, v0, v1
	ds_swizzle_b32 v0, v23 offset:swizzle(SWAP,8)
	v_max3_f32 v37, v5, |v202|, |v1|
	ds_swizzle_b32 v1, v37 offset:swizzle(SWAP,8)
	v_max3_f32 v38, v40, |v199|, |v2|
	v_cvt_pk_bf16_f32 v5, v2, v3
	s_waitcnt lgkmcnt(1)
	v_max_f32_e32 v0, v0, v0
	v_max_f32_e32 v0, v23, v0
	ds_swizzle_b32 v23, v0 offset:swizzle(SWAP,16)
	s_waitcnt lgkmcnt(1)
	v_max_f32_e32 v1, v1, v1
	v_max_f32_e32 v1, v37, v1
	ds_swizzle_b32 v2, v38 offset:swizzle(SWAP,8)
	ds_swizzle_b32 v3, v39 offset:swizzle(SWAP,8)
	s_waitcnt lgkmcnt(2)
	v_max_f32_e32 v23, v23, v23
	v_max_f32_e32 v0, v0, v23
	ds_swizzle_b32 v23, v1 offset:swizzle(SWAP,16)
	s_waitcnt lgkmcnt(2)
	v_max_f32_e32 v2, v2, v2
	v_max_f32_e32 v2, v38, v2
	s_waitcnt lgkmcnt(1)
	v_max_f32_e32 v3, v3, v3
	v_max_f32_e32 v3, v39, v3
	s_waitcnt lgkmcnt(0)
	v_max_f32_e32 v23, v23, v23
	v_max_f32_e32 v1, v1, v23
	ds_swizzle_b32 v23, v2 offset:swizzle(SWAP,16)
	v_mov_b32_e32 v37, v1
	s_nop 1
	v_permlane32_swap_b32_e32 v1, v37
	s_waitcnt lgkmcnt(0)
	v_max_f32_e32 v23, v23, v23
	v_max_f32_e32 v2, v2, v23
	ds_swizzle_b32 v23, v3 offset:swizzle(SWAP,16)
	v_mov_b32_e32 v38, v2
	s_nop 1
	v_permlane32_swap_b32_e32 v2, v38
	s_waitcnt lgkmcnt(0)
	v_max_f32_e32 v23, v23, v23
	v_max_f32_e32 v3, v3, v23
	v_mov_b32_e32 v23, v0
	v_mov_b32_e32 v39, v3
	s_nop 0
	v_permlane32_swap_b32_e32 v0, v23
	v_permlane32_swap_b32_e32 v3, v39
	s_and_saveexec_b64 s[28:29], s[4:5]
	s_cbranch_execz .LBB0_25
	v_max_f32_e32 v0, v0, v0
	v_max_f32_e32 v23, v23, v23
	v_max_f32_e32 v0, v0, v23
	v_max_f32_e32 v1, v1, v1
	v_max_f32_e32 v23, v37, v37
	v_max_f32_e32 v1, v1, v23
	v_max_f32_e32 v2, v2, v2
	v_max_f32_e32 v23, v38, v38
	v_max_f32_e32 v2, v2, v23
	v_max_f32_e32 v3, v3, v3
	v_max_f32_e32 v23, v39, v39
	v_max_f32_e32 v3, v3, v23
	ds_write_b128 v85, v[0:3]

.LBB0_34:
	v_readlane_b32 s4, v247, 0
	s_mul_hi_u32 s4, s4, 0x164
	s_mul_i32 s4, s4, s65
	s_sub_i32 s4, 0x164, s4
	s_sub_i32 s5, s4, s65
	s_cmp_ge_u32 s4, s65
	s_cselect_b32 s4, s5, s4
	s_sub_i32 s5, s4, s65
	s_cmp_ge_u32 s4, s65
	s_cselect_b32 s4, s5, s4
	s_sub_i32 s5, s64, s4
	s_cmp_lg_u32 s4, 0
	s_cselect_b32 s8, s5, 0
	s_cmpk_lt_i32 s8, 0x15c
	s_mul_i32 s5, s8, 53
	s_cselect_b32 s34, s5, 0
	s_mul_i32 s5, s3, 0x2100
	s_add_i32 s5, s5, 0
	s_load_dwordx2 s[22:23], s[20:21], 0x18
	s_load_dwordx2 s[24:25], s[20:21], 0x78
	s_add_u32 s20, s18, 0x400000
	s_addc_u32 s21, s19, 0
	s_add_u32 s26, s18, 0x11800000
	s_addc_u32 s27, s19, 0
	s_add_u32 s28, s18, 0x78000
	s_addc_u32 s29, s19, 0
	s_cmp_lt_i32 s34, 1
	s_cselect_b64 s[6:7], -1, 0
	s_cmp_lt_i32 s2, s4
	s_cselect_b64 s[10:11], -1, 0
	s_or_b64 s[6:7], s[6:7], s[10:11]
	s_and_b64 vcc, exec, s[6:7]
	v_writelane_b32 v247, s5, 3
	s_cbranch_vccnz .LBB0_84
	s_sub_i32 s4, s2, s4
	s_lshl_b32 s9, s4, 3
	s_add_i32 s9, s9, s3
	s_cmp_ge_i32 s9, s34
	s_cbranch_scc1 .LBB0_84
	s_cmpk_gt_i32 s9, 0x47ff
	s_cbranch_scc0 .LBB0_39
	s_add_i32 s4, s9, 0xffffb800
	s_lshr_b32 s4, s4, 1
	s_and_b32 s42, s4, 0x7fffffc0
	s_lshl_b32 s4, s9, 5
	s_and_b32 s36, s4, 0xfe0
	s_waitcnt lgkmcnt(0)
	s_mov_b64 s[4:5], s[24:25]
	s_mov_b32 s43, 1
	s_cbranch_execz .LBB0_40
	s_mov_b64 s[6:7], 0x1000
	s_movk_i32 s67, 0x2b00
	v_mov_b32_e32 v70, 0x3d000000
	s_mov_b64 s[48:49], s[26:27]
	s_mov_b64 s[38:39], s[28:29]
	s_branch .LBB0_41

.LBB0_236:
	v_readlane_b32 s4, v247, 0
	s_mul_hi_u32 s4, s4, 0xda4
	s_mul_i32 s4, s4, s65
	s_sub_i32 s4, 0xda4, s4
	s_sub_i32 s5, s4, s65
	s_cmp_ge_u32 s4, s65
	s_cselect_b32 s4, s5, s4
	s_sub_i32 s5, s4, s65
	s_cmp_ge_u32 s4, s65
	s_cselect_b32 s10, s5, s4
	s_cmp_eq_u32 s10, 0
	s_cselect_b64 s[4:5], -1, 0
	s_cmp_ge_i32 s66, s10
	s_cselect_b64 s[8:9], -1, 0
	s_or_b64 s[14:15], s[8:9], s[4:5]
	s_andn2_b64 vcc, exec, s[14:15]
	s_cbranch_vccnz .LBB0_245
	s_xor_b64 s[4:5], s[4:5], -1
	s_and_b64 s[4:5], s[8:9], s[4:5]
	s_and_b64 s[4:5], s[4:5], exec
	s_cselect_b32 s4, s10, 0
	s_mov_b32 s8, 0
	s_sub_i32 s5, s66, s4
	s_add_i32 s20, s5, 0xe4
	v_mbcnt_lo_u32_b32 v0, -1, s8
	v_mbcnt_hi_u32_b32 v0, -1, v0
	s_cmpk_gt_i32 s20, 0x2af
	s_cbranch_scc1 .LBB0_245
	v_lshlrev_b32_e32 v1, 3, v0
	v_and_b32_e32 v2, 0xffffffc0, v1
	s_sub_i32 s21, s64, s4
	v_add_u32_e32 v1, s63, v2
	s_mov_b32 s4, 0xac00
	v_mad_i64_i32 v[64:65], s[4:5], v1, s4, 0
	v_lshlrev_b32_e32 v1, 2, v0
	v_and_b32_e32 v66, 28, v1
	s_load_dwordx4 s[8:11], s[6:7], 0x68
	v_cmp_gt_u32_e64 s[4:5], 8, v0
	v_lshlrev_b32_e32 v68, 2, v66
	s_add_i32 s6, 0, 0x16000
	v_mov_b32_e32 v69, 0
	s_waitcnt vmcnt(0)
	v_add_u32_e32 v76, s6, v68
	s_and_b64 s[6:7], s[40:41], s[4:5]
	s_waitcnt lgkmcnt(0)
	v_lshl_add_u64 v[0:1], s[12:13], 0, v[68:69]
	s_add_u32 s12, s12, s63
	s_mov_b64 s[14:15], 0xa0000
	s_addc_u32 s13, s13, 0
	v_ashrrev_i32_e32 v3, 31, v2
	v_writelane_b32 v247, s84, 1
	v_lshl_add_u64 v[70:71], v[0:1], 0, s[14:15]
	v_lshl_add_u64 v[0:1], s[12:13], 0, v[2:3]
	s_mov_b64 s[12:13], 0x6c00000
	v_writelane_b32 v247, s85, 2
	v_add_u32_e32 v67, s72, v68
	v_lshl_add_u64 v[72:73], v[0:1], 0, s[12:13]
	v_lshlrev_b32_e32 v68, 2, v66
	s_mov_b32 s13, 0x2b000
	s_mov_b32 s22, 0x35000
	s_mov_b32 s23, 0x40000
	s_mov_b32 s24, 0x4b000
	s_mov_b32 s25, 0x56000
	s_mov_b32 s26, 0x60000
	s_mov_b32 s27, 0x6b000
	s_mov_b32 s28, 0x76000
	s_mov_b32 s29, 0x81000
	s_mov_b32 s30, 0x8b000
	s_mov_b32 s31, 0x96000
	s_mov_b32 s34, 0xa1000
	s_mov_b32 s35, 0xac000
	s_mov_b32 s36, 0xb6000
	s_mov_b32 s37, 0xc1000
	s_mov_b32 s38, 0xcc000
	s_mov_b32 s39, 0xd7000
	s_mov_b32 s45, 0xe1000
	s_mov_b32 s46, 0xec000
	s_mov_b32 s47, 0xf7000
	s_mov_b32 s48, 0x102000
	s_mov_b32 s49, 0x10c000
	s_mov_b32 s50, 0x117000
	s_mov_b32 s51, 0x122000
	s_mov_b32 s52, 0x12d000
	s_mov_b32 s53, 0x137000
	s_mov_b32 s54, 0x142000
	s_mov_b32 s55, 0x14d000
	s_mov_b32 s56, 0x158000
	s_mov_b32 s57, 0x162000
	s_mov_b32 s58, 0x16d000
	s_mov_b32 s59, 0x178000
	s_mov_b32 s60, 0x183000
	s_mov_b32 s61, 0x18d000
	s_mov_b32 s62, 0x198000
	s_mov_b32 s63, 0x1a3000
	s_mov_b32 s68, 0x1ae000
	s_mov_b32 s69, 0x1b8000
	s_mov_b32 s70, 0x1c3000
	s_mov_b32 s71, 0x1ce000
	s_mov_b32 s72, 0x1d9000
	s_mov_b32 s73, 0x1e3000
	s_mov_b32 s74, 0x1ee000
	s_mov_b32 s75, 0x1f9000
	s_mov_b32 s76, 0x204000
	s_mov_b32 s77, 0x20e000
	s_mov_b32 s78, 0x219000
	s_mov_b32 s79, 0x224000
	s_mov_b32 s80, 0x22f000
	s_mov_b32 s81, 0x239000
	s_mov_b32 s82, 0x244000
	s_mov_b32 s83, 0x24f000
	s_mov_b32 s84, 0x25a000
	s_mov_b32 s85, 0x264000
	s_mov_b32 s86, 0x26f000
	s_mov_b32 s87, 0x27a000
	s_mov_b32 s88, 0x285000
	s_mov_b32 s89, 0x28f000
	s_mov_b32 s90, 0x29a000
	s_mov_b32 s91, 0x2a5000
	s_mov_b32 s12, 0x3f808000
	s_mov_b32 s92, 0x42fe0000
	s_mov_b32 s93, 0xc0c0400
	s_mov_b32 s94, 0x5040100
	s_movk_i32 s95, 0x1000
	s_movk_i32 s96, 0x2000
	s_movk_i32 s97, 0x3000
	s_branch .LBB0_240
